# adds: P4/P6 residual tile prefetched into LDS by the last K-iteration's otherwise dead staging DMAs, epilogue reads it with ds_read
# speedup vs baseline: 1.0195x; 1.0086x over previous
.LBB0_567:
	v_add_u32_e32 v153, s71, v151
	ds_read_b128 v[154:157], v153
	ds_read_b128 v[158:161], v153 offset:1024
	ds_read_b128 v[162:165], v153 offset:2048
	ds_read_b128 v[166:169], v153 offset:3072
	v_add_u32_e32 v153, s72, v151
	s_add_u32 s42, s10, s40
	ds_read_b128 v[170:173], v153
	ds_read_b128 v[174:177], v153 offset:1024
	ds_read_b128 v[178:181], v153 offset:2048
	ds_read_b128 v[182:185], v153 offset:3072
	s_addc_u32 s43, s11, s41
	s_add_u32 s42, s42, 0x100
	s_addc_u32 s43, s43, 0
	s_add_u32 s76, s0, s40
	s_addc_u32 s77, s29, s41
	s_cmpk_eq_i32 s40, 0x700
	s_cselect_b32 s45, s21, s43
	s_cselect_b32 s44, s73, s42
	s_cselect_b32 s43, s19, s77
	s_cselect_b32 s42, s74, s76
	v_lshl_add_u64 v[214:215], v[146:147], 0, s[40:41]
	s_add_i32 m0, s17, 0xc000
	ds_read_b128 v[186:189], v152
	ds_read_b128 v[190:193], v152 offset:1024
	ds_read_b128 v[194:197], v152 offset:2048
	ds_read_b128 v[198:201], v152 offset:3072
	ds_read_b128 v[202:205], v152 offset:4096
	ds_read_b128 v[206:209], v152 offset:5120
	ds_read_b128 v[210:213], v152 offset:6144
	ds_read_b128 v[220:223], v152 offset:7168
	global_load_lds_dwordx4 v[214:215], off
	v_lshl_add_u64 v[214:215], v[148:149], 0, s[40:41]
	s_add_i32 m0, s17, 0xe000
	s_nop 0
	global_load_lds_dwordx4 v[214:215], off
	s_waitcnt vmcnt(8)
	s_waitcnt lgkmcnt(0)
	s_setprio 1
	s_waitcnt lgkmcnt(0)
	v_mfma_f32_16x16x32_bf16 v[126:129], v[154:157], v[186:189], v[126:129]
	s_barrier
	v_mfma_f32_16x16x32_bf16 v[122:125], v[162:165], v[186:189], v[122:125]
	v_mfma_f32_16x16x32_bf16 v[110:113], v[154:157], v[194:197], v[110:113]
	v_mfma_f32_16x16x32_bf16 v[106:109], v[162:165], v[194:197], v[106:109]
	v_mfma_f32_16x16x32_bf16 v[94:97], v[154:157], v[202:205], v[94:97]
	v_mfma_f32_16x16x32_bf16 v[90:93], v[162:165], v[202:205], v[90:93]
	v_mfma_f32_16x16x32_bf16 v[78:81], v[154:157], v[210:213], v[78:81]
	v_mfma_f32_16x16x32_bf16 v[74:77], v[162:165], v[210:213], v[74:77]
	v_mfma_f32_16x16x32_bf16 v[118:121], v[170:173], v[186:189], v[118:121]
	v_mfma_f32_16x16x32_bf16 v[114:117], v[178:181], v[186:189], v[114:117]
	v_mfma_f32_16x16x32_bf16 v[102:105], v[170:173], v[194:197], v[102:105]
	v_mfma_f32_16x16x32_bf16 v[98:101], v[178:181], v[194:197], v[98:101]
	v_mfma_f32_16x16x32_bf16 v[86:89], v[170:173], v[202:205], v[86:89]
	v_mfma_f32_16x16x32_bf16 v[82:85], v[178:181], v[202:205], v[82:85]
	v_mfma_f32_16x16x32_bf16 v[70:73], v[170:173], v[210:213], v[70:73]
	v_mfma_f32_16x16x32_bf16 v[66:69], v[178:181], v[210:213], v[66:69]
	v_mfma_f32_16x16x32_bf16 v[126:129], v[158:161], v[190:193], v[126:129]
	v_mfma_f32_16x16x32_bf16 v[122:125], v[166:169], v[190:193], v[122:125]
	v_mfma_f32_16x16x32_bf16 v[110:113], v[158:161], v[198:201], v[110:113]
	v_mfma_f32_16x16x32_bf16 v[106:109], v[166:169], v[198:201], v[106:109]
	v_mfma_f32_16x16x32_bf16 v[94:97], v[158:161], v[206:209], v[94:97]
	v_mfma_f32_16x16x32_bf16 v[90:93], v[166:169], v[206:209], v[90:93]
	v_mfma_f32_16x16x32_bf16 v[78:81], v[158:161], v[220:223], v[78:81]
	v_mfma_f32_16x16x32_bf16 v[74:77], v[166:169], v[220:223], v[74:77]
	v_mfma_f32_16x16x32_bf16 v[118:121], v[174:177], v[190:193], v[118:121]
	v_mfma_f32_16x16x32_bf16 v[114:117], v[182:185], v[190:193], v[114:117]
	v_mfma_f32_16x16x32_bf16 v[102:105], v[174:177], v[198:201], v[102:105]
	v_mfma_f32_16x16x32_bf16 v[98:101], v[182:185], v[198:201], v[98:101]
	v_mfma_f32_16x16x32_bf16 v[86:89], v[174:177], v[206:209], v[86:89]
	v_mfma_f32_16x16x32_bf16 v[82:85], v[182:185], v[206:209], v[82:85]
	v_mfma_f32_16x16x32_bf16 v[70:73], v[174:177], v[220:223], v[70:73]
	v_mfma_f32_16x16x32_bf16 v[66:69], v[182:185], v[220:223], v[66:69]
	s_setprio 0
	s_barrier
	s_add_i32 s76, s71, s49
	v_lshl_add_u64 v[214:215], s[42:43], 0, v[132:133]
	s_mov_b32 m0, s76
	ds_read_b128 v[186:189], v152 offset:16384
	ds_read_b128 v[190:193], v152 offset:17408
	ds_read_b128 v[194:197], v152 offset:18432
	ds_read_b128 v[198:201], v152 offset:19456
	ds_read_b128 v[202:205], v152 offset:20480
	ds_read_b128 v[206:209], v152 offset:21504
	ds_read_b128 v[210:213], v152 offset:22528
	ds_read_b128 v[220:223], v152 offset:23552
	global_load_lds_dwordx4 v[214:215], off
	s_add_i32 m0, s76, 0x2000
	s_add_u32 s76, s42, 0x40000
	v_lshl_add_u64 v[224:225], s[42:43], 0, v[136:137]
	s_addc_u32 s77, s43, 0
	s_add_i32 s78, s72, s49
	global_load_lds_dwordx4 v[224:225], off
	v_lshl_add_u64 v[226:227], s[76:77], 0, v[132:133]
	s_mov_b32 m0, s78
	v_lshl_add_u64 v[228:229], s[44:45], 0, v[134:135]
	global_load_lds_dwordx4 v[226:227], off
	v_lshl_add_u64 v[226:227], s[76:77], 0, v[136:137]
	s_add_i32 m0, s78, 0x2000
	s_nop 0
	global_load_lds_dwordx4 v[226:227], off
	v_lshl_add_u64 v[226:227], s[44:45], 0, v[130:131]
	s_mov_b32 m0, s17
	s_nop 0
	global_load_lds_dwordx4 v[226:227], off
	s_mov_b32 m0, s50
	s_nop 0
	global_load_lds_dwordx4 v[228:229], off
	s_waitcnt vmcnt(8)
	s_waitcnt lgkmcnt(0)
	s_setprio 1
	s_waitcnt lgkmcnt(0)
	v_mfma_f32_16x16x32_bf16 v[62:65], v[154:157], v[186:189], v[62:65]
	s_barrier
	v_mfma_f32_16x16x32_bf16 v[58:61], v[162:165], v[186:189], v[58:61]
	v_mfma_f32_16x16x32_bf16 v[46:49], v[154:157], v[194:197], v[46:49]
	v_mfma_f32_16x16x32_bf16 v[42:45], v[162:165], v[194:197], v[42:45]
	v_mfma_f32_16x16x32_bf16 v[30:33], v[154:157], v[202:205], v[30:33]
	v_mfma_f32_16x16x32_bf16 v[26:29], v[162:165], v[202:205], v[26:29]
	v_mfma_f32_16x16x32_bf16 v[14:17], v[154:157], v[210:213], v[14:17]
	v_mfma_f32_16x16x32_bf16 v[10:13], v[162:165], v[210:213], v[10:13]
	v_mfma_f32_16x16x32_bf16 v[54:57], v[170:173], v[186:189], v[54:57]
	v_mfma_f32_16x16x32_bf16 v[50:53], v[178:181], v[186:189], v[50:53]
	v_mfma_f32_16x16x32_bf16 v[38:41], v[170:173], v[194:197], v[38:41]
	v_mfma_f32_16x16x32_bf16 v[34:37], v[178:181], v[194:197], v[34:37]
	v_mfma_f32_16x16x32_bf16 v[22:25], v[170:173], v[202:205], v[22:25]
	v_mfma_f32_16x16x32_bf16 v[18:21], v[178:181], v[202:205], v[18:21]
	v_mfma_f32_16x16x32_bf16 v[6:9], v[170:173], v[210:213], v[6:9]
	v_mfma_f32_16x16x32_bf16 v[2:5], v[178:181], v[210:213], v[2:5]
	v_mfma_f32_16x16x32_bf16 v[62:65], v[158:161], v[190:193], v[62:65]
	v_mfma_f32_16x16x32_bf16 v[58:61], v[166:169], v[190:193], v[58:61]
	v_mfma_f32_16x16x32_bf16 v[46:49], v[158:161], v[198:201], v[46:49]
	v_mfma_f32_16x16x32_bf16 v[42:45], v[166:169], v[198:201], v[42:45]
	v_mfma_f32_16x16x32_bf16 v[30:33], v[158:161], v[206:209], v[30:33]
	v_mfma_f32_16x16x32_bf16 v[26:29], v[166:169], v[206:209], v[26:29]
	v_mfma_f32_16x16x32_bf16 v[14:17], v[158:161], v[220:223], v[14:17]
	v_mfma_f32_16x16x32_bf16 v[10:13], v[166:169], v[220:223], v[10:13]
	v_mfma_f32_16x16x32_bf16 v[54:57], v[174:177], v[190:193], v[54:57]
	v_mfma_f32_16x16x32_bf16 v[50:53], v[182:185], v[190:193], v[50:53]
	v_mfma_f32_16x16x32_bf16 v[38:41], v[174:177], v[198:201], v[38:41]
	v_mfma_f32_16x16x32_bf16 v[34:37], v[182:185], v[198:201], v[34:37]
	v_mfma_f32_16x16x32_bf16 v[22:25], v[174:177], v[206:209], v[22:25]
	v_mfma_f32_16x16x32_bf16 v[18:21], v[182:185], v[206:209], v[18:21]
	v_mfma_f32_16x16x32_bf16 v[6:9], v[174:177], v[220:223], v[6:9]
	v_mfma_f32_16x16x32_bf16 v[2:5], v[182:185], v[220:223], v[2:5]
	s_setprio 0
	s_barrier
	s_add_i32 s76, 0, 0x18000
	v_add_u32_e32 v153, s76, v151
	s_add_i32 s77, 0, 0x1c000
	ds_read_b128 v[154:157], v153
	ds_read_b128 v[158:161], v153 offset:1024
	ds_read_b128 v[162:165], v153 offset:2048
	ds_read_b128 v[166:169], v153 offset:3072
	v_add_u32_e32 v153, s77, v151
	ds_read_b128 v[170:173], v153
	ds_read_b128 v[174:177], v153 offset:1024
	ds_read_b128 v[178:181], v153 offset:2048
	ds_read_b128 v[182:185], v153 offset:3072
	s_add_u32 s44, s44, 0x40000
	s_addc_u32 s45, s45, 0
	s_mov_b32 m0, s51
	v_lshl_add_u64 v[230:231], s[44:45], 0, v[130:131]
	ds_read_b128 v[186:189], v152 offset:32768
	ds_read_b128 v[190:193], v152 offset:33792
	ds_read_b128 v[194:197], v152 offset:34816
	ds_read_b128 v[198:201], v152 offset:35840
	ds_read_b128 v[202:205], v152 offset:36864
	ds_read_b128 v[206:209], v152 offset:37888
	ds_read_b128 v[210:213], v152 offset:38912
	ds_read_b128 v[220:223], v152 offset:39936
	global_load_lds_dwordx4 v[230:231], off
	v_lshl_add_u64 v[230:231], s[44:45], 0, v[134:135]
	s_mov_b32 m0, s60
	s_nop 0
	global_load_lds_dwordx4 v[230:231], off
	s_waitcnt vmcnt(8)
	s_waitcnt lgkmcnt(0)
	s_setprio 1
	s_waitcnt lgkmcnt(0)
	v_mfma_f32_16x16x32_bf16 v[126:129], v[154:157], v[186:189], v[126:129]
	s_barrier
	v_mfma_f32_16x16x32_bf16 v[122:125], v[162:165], v[186:189], v[122:125]
	v_mfma_f32_16x16x32_bf16 v[110:113], v[154:157], v[194:197], v[110:113]
	v_mfma_f32_16x16x32_bf16 v[106:109], v[162:165], v[194:197], v[106:109]
	v_mfma_f32_16x16x32_bf16 v[94:97], v[154:157], v[202:205], v[94:97]
	v_mfma_f32_16x16x32_bf16 v[90:93], v[162:165], v[202:205], v[90:93]
	v_mfma_f32_16x16x32_bf16 v[78:81], v[154:157], v[210:213], v[78:81]
	v_mfma_f32_16x16x32_bf16 v[74:77], v[162:165], v[210:213], v[74:77]
	v_mfma_f32_16x16x32_bf16 v[118:121], v[170:173], v[186:189], v[118:121]
	v_mfma_f32_16x16x32_bf16 v[114:117], v[178:181], v[186:189], v[114:117]
	v_mfma_f32_16x16x32_bf16 v[102:105], v[170:173], v[194:197], v[102:105]
	v_mfma_f32_16x16x32_bf16 v[98:101], v[178:181], v[194:197], v[98:101]
	v_mfma_f32_16x16x32_bf16 v[86:89], v[170:173], v[202:205], v[86:89]
	v_mfma_f32_16x16x32_bf16 v[82:85], v[178:181], v[202:205], v[82:85]
	v_mfma_f32_16x16x32_bf16 v[70:73], v[170:173], v[210:213], v[70:73]
	v_mfma_f32_16x16x32_bf16 v[66:69], v[178:181], v[210:213], v[66:69]
	v_mfma_f32_16x16x32_bf16 v[126:129], v[158:161], v[190:193], v[126:129]
	v_mfma_f32_16x16x32_bf16 v[122:125], v[166:169], v[190:193], v[122:125]
	v_mfma_f32_16x16x32_bf16 v[110:113], v[158:161], v[198:201], v[110:113]
	v_mfma_f32_16x16x32_bf16 v[106:109], v[166:169], v[198:201], v[106:109]
	v_mfma_f32_16x16x32_bf16 v[94:97], v[158:161], v[206:209], v[94:97]
	v_mfma_f32_16x16x32_bf16 v[90:93], v[166:169], v[206:209], v[90:93]
	v_mfma_f32_16x16x32_bf16 v[78:81], v[158:161], v[220:223], v[78:81]
	v_mfma_f32_16x16x32_bf16 v[74:77], v[166:169], v[220:223], v[74:77]
	v_mfma_f32_16x16x32_bf16 v[118:121], v[174:177], v[190:193], v[118:121]
	v_mfma_f32_16x16x32_bf16 v[114:117], v[182:185], v[190:193], v[114:117]
	v_mfma_f32_16x16x32_bf16 v[102:105], v[174:177], v[198:201], v[102:105]
	v_mfma_f32_16x16x32_bf16 v[98:101], v[182:185], v[198:201], v[98:101]
	v_mfma_f32_16x16x32_bf16 v[86:89], v[174:177], v[206:209], v[86:89]
	v_mfma_f32_16x16x32_bf16 v[82:85], v[182:185], v[206:209], v[82:85]
	v_mfma_f32_16x16x32_bf16 v[70:73], v[174:177], v[220:223], v[70:73]
	v_mfma_f32_16x16x32_bf16 v[66:69], v[182:185], v[220:223], v[66:69]
	s_setprio 0
	s_barrier
	s_add_i32 s44, s76, s49
	v_lshl_add_u64 v[214:215], v[214:215], 0, s[12:13]
	s_mov_b32 m0, s44
	ds_read_b128 v[186:189], v152 offset:49152
	ds_read_b128 v[190:193], v152 offset:50176
	ds_read_b128 v[194:197], v152 offset:51200
	ds_read_b128 v[198:201], v152 offset:52224
	ds_read_b128 v[202:205], v152 offset:53248
	ds_read_b128 v[206:209], v152 offset:54272
	ds_read_b128 v[210:213], v152 offset:55296
	ds_read_b128 v[220:223], v152 offset:56320
	global_load_lds_dwordx4 v[214:215], off
	s_add_i32 m0, s44, 0x2000
	s_add_u32 s42, s42, 0x40080
	v_lshl_add_u64 v[214:215], v[224:225], 0, s[12:13]
	s_addc_u32 s43, s43, 0
	s_add_i32 s44, s77, s49
	global_load_lds_dwordx4 v[214:215], off
	v_lshl_add_u64 v[214:215], s[42:43], 0, v[132:133]
	s_mov_b32 m0, s44
	s_nop 0
	global_load_lds_dwordx4 v[214:215], off
	v_lshl_add_u64 v[214:215], s[42:43], 0, v[136:137]
	s_add_i32 m0, s44, 0x2000
	s_nop 0
	global_load_lds_dwordx4 v[214:215], off
	v_lshl_add_u64 v[214:215], v[226:227], 0, s[12:13]
	s_mov_b32 m0, s68
	s_nop 0
	global_load_lds_dwordx4 v[214:215], off
	v_lshl_add_u64 v[214:215], v[228:229], 0, s[12:13]
	s_mov_b32 m0, s69
	s_nop 0
	global_load_lds_dwordx4 v[214:215], off
	s_waitcnt vmcnt(8)
	s_waitcnt lgkmcnt(0)
	s_setprio 1
	s_waitcnt lgkmcnt(0)
	v_mfma_f32_16x16x32_bf16 v[62:65], v[154:157], v[186:189], v[62:65]
	s_barrier
	v_mfma_f32_16x16x32_bf16 v[58:61], v[162:165], v[186:189], v[58:61]
	v_mfma_f32_16x16x32_bf16 v[46:49], v[154:157], v[194:197], v[46:49]
	v_mfma_f32_16x16x32_bf16 v[42:45], v[162:165], v[194:197], v[42:45]
	v_mfma_f32_16x16x32_bf16 v[30:33], v[154:157], v[202:205], v[30:33]
	v_mfma_f32_16x16x32_bf16 v[26:29], v[162:165], v[202:205], v[26:29]
	v_mfma_f32_16x16x32_bf16 v[14:17], v[154:157], v[210:213], v[14:17]
	v_mfma_f32_16x16x32_bf16 v[10:13], v[162:165], v[210:213], v[10:13]
	v_mfma_f32_16x16x32_bf16 v[54:57], v[170:173], v[186:189], v[54:57]
	v_mfma_f32_16x16x32_bf16 v[50:53], v[178:181], v[186:189], v[50:53]
	v_mfma_f32_16x16x32_bf16 v[38:41], v[170:173], v[194:197], v[38:41]
	v_mfma_f32_16x16x32_bf16 v[34:37], v[178:181], v[194:197], v[34:37]
	v_mfma_f32_16x16x32_bf16 v[22:25], v[170:173], v[202:205], v[22:25]
	v_mfma_f32_16x16x32_bf16 v[18:21], v[178:181], v[202:205], v[18:21]
	v_mfma_f32_16x16x32_bf16 v[6:9], v[170:173], v[210:213], v[6:9]
	v_mfma_f32_16x16x32_bf16 v[2:5], v[178:181], v[210:213], v[2:5]
	v_mfma_f32_16x16x32_bf16 v[62:65], v[158:161], v[190:193], v[62:65]
	v_mfma_f32_16x16x32_bf16 v[58:61], v[166:169], v[190:193], v[58:61]
	v_mfma_f32_16x16x32_bf16 v[46:49], v[158:161], v[198:201], v[46:49]
	v_mfma_f32_16x16x32_bf16 v[42:45], v[166:169], v[198:201], v[42:45]
	v_mfma_f32_16x16x32_bf16 v[30:33], v[158:161], v[206:209], v[30:33]
	v_mfma_f32_16x16x32_bf16 v[26:29], v[166:169], v[206:209], v[26:29]
	v_mfma_f32_16x16x32_bf16 v[14:17], v[158:161], v[220:223], v[14:17]
	v_mfma_f32_16x16x32_bf16 v[10:13], v[166:169], v[220:223], v[10:13]
	v_mfma_f32_16x16x32_bf16 v[54:57], v[174:177], v[190:193], v[54:57]
	v_mfma_f32_16x16x32_bf16 v[50:53], v[182:185], v[190:193], v[50:53]
	v_mfma_f32_16x16x32_bf16 v[38:41], v[174:177], v[198:201], v[38:41]
	v_mfma_f32_16x16x32_bf16 v[34:37], v[182:185], v[198:201], v[34:37]
	v_mfma_f32_16x16x32_bf16 v[22:25], v[174:177], v[206:209], v[22:25]
	v_mfma_f32_16x16x32_bf16 v[18:21], v[182:185], v[206:209], v[18:21]
	v_mfma_f32_16x16x32_bf16 v[6:9], v[174:177], v[220:223], v[6:9]
	v_mfma_f32_16x16x32_bf16 v[2:5], v[182:185], v[220:223], v[2:5]
	s_setprio 0
	s_barrier
	s_add_i32 s75, s75, 2
	s_add_u32 s40, s40, 0x100
	s_addc_u32 s41, s41, 0
	s_cmp_gt_u32 s75, 11
	s_cbranch_scc0 .LBB0_567
	s_lshl_b32 s82, s14, 19
	s_lshl_b32 s83, s16, 9
	s_add_u32 s80, s38, s82
	s_addc_u32 s81, s39, 0
	s_add_u32 s80, s80, s83
	s_addc_u32 s81, s81, 0
	v_and_b32_e32 v232, 15, v1
	s_lshr_b32 s82, s48, 2
	s_lshl_b32 s82, s82, 6
	v_lshrrev_b32_e32 v233, 4, v1
	v_add_u32_e32 v232, s82, v232
	s_and_b32 s83, s48, 3
	v_lshlrev_b32_e32 v233, 4, v233
	s_lshl_b32 s83, s83, 6
	v_lshlrev_b32_e32 v232, 11, v232
	v_add3_u32 v232, v232, v233, s83
	v_add_u32_e32 v153, s71, v151
	ds_read_b128 v[154:157], v153
	ds_read_b128 v[158:161], v153 offset:1024
	ds_read_b128 v[162:165], v153 offset:2048
	ds_read_b128 v[166:169], v153 offset:3072
	v_add_u32_e32 v153, s72, v151
	s_add_u32 s42, s10, s40
	ds_read_b128 v[170:173], v153
	ds_read_b128 v[174:177], v153 offset:1024
	ds_read_b128 v[178:181], v153 offset:2048
	ds_read_b128 v[182:185], v153 offset:3072
	s_addc_u32 s43, s11, s41
	s_add_u32 s42, s42, 0x100
	s_addc_u32 s43, s43, 0
	s_add_u32 s76, s0, s40
	s_addc_u32 s77, s29, s41
	s_cmpk_eq_i32 s40, 0x700
	s_cselect_b32 s45, s21, s43
	s_cselect_b32 s44, s73, s42
	s_cselect_b32 s43, s19, s77
	s_cselect_b32 s42, s74, s76
	v_lshl_add_u64 v[214:215], v[146:147], 0, s[40:41]
	s_add_i32 m0, s17, 0xc000
	ds_read_b128 v[186:189], v152
	ds_read_b128 v[190:193], v152 offset:1024
	ds_read_b128 v[194:197], v152 offset:2048
	ds_read_b128 v[198:201], v152 offset:3072
	ds_read_b128 v[202:205], v152 offset:4096
	ds_read_b128 v[206:209], v152 offset:5120
	ds_read_b128 v[210:213], v152 offset:6144
	ds_read_b128 v[220:223], v152 offset:7168
	global_load_lds_dwordx4 v[214:215], off
	v_lshl_add_u64 v[214:215], v[148:149], 0, s[40:41]
	s_add_i32 m0, s17, 0xe000
	s_nop 0
	global_load_lds_dwordx4 v[214:215], off
	s_waitcnt vmcnt(8)
	s_waitcnt lgkmcnt(0)
	s_setprio 1
	s_waitcnt lgkmcnt(0)
	v_mfma_f32_16x16x32_bf16 v[126:129], v[154:157], v[186:189], v[126:129]
	s_barrier
	v_mfma_f32_16x16x32_bf16 v[122:125], v[162:165], v[186:189], v[122:125]
	v_mfma_f32_16x16x32_bf16 v[110:113], v[154:157], v[194:197], v[110:113]
	v_mfma_f32_16x16x32_bf16 v[106:109], v[162:165], v[194:197], v[106:109]
	v_mfma_f32_16x16x32_bf16 v[94:97], v[154:157], v[202:205], v[94:97]
	v_mfma_f32_16x16x32_bf16 v[90:93], v[162:165], v[202:205], v[90:93]
	v_mfma_f32_16x16x32_bf16 v[78:81], v[154:157], v[210:213], v[78:81]
	v_mfma_f32_16x16x32_bf16 v[74:77], v[162:165], v[210:213], v[74:77]
	v_mfma_f32_16x16x32_bf16 v[118:121], v[170:173], v[186:189], v[118:121]
	v_mfma_f32_16x16x32_bf16 v[114:117], v[178:181], v[186:189], v[114:117]
	v_mfma_f32_16x16x32_bf16 v[102:105], v[170:173], v[194:197], v[102:105]
	v_mfma_f32_16x16x32_bf16 v[98:101], v[178:181], v[194:197], v[98:101]
	v_mfma_f32_16x16x32_bf16 v[86:89], v[170:173], v[202:205], v[86:89]
	v_mfma_f32_16x16x32_bf16 v[82:85], v[178:181], v[202:205], v[82:85]
	v_mfma_f32_16x16x32_bf16 v[70:73], v[170:173], v[210:213], v[70:73]
	v_mfma_f32_16x16x32_bf16 v[66:69], v[178:181], v[210:213], v[66:69]
	v_mfma_f32_16x16x32_bf16 v[126:129], v[158:161], v[190:193], v[126:129]
	v_mfma_f32_16x16x32_bf16 v[122:125], v[166:169], v[190:193], v[122:125]
	v_mfma_f32_16x16x32_bf16 v[110:113], v[158:161], v[198:201], v[110:113]
	v_mfma_f32_16x16x32_bf16 v[106:109], v[166:169], v[198:201], v[106:109]
	v_mfma_f32_16x16x32_bf16 v[94:97], v[158:161], v[206:209], v[94:97]
	v_mfma_f32_16x16x32_bf16 v[90:93], v[166:169], v[206:209], v[90:93]
	v_mfma_f32_16x16x32_bf16 v[78:81], v[158:161], v[220:223], v[78:81]
	v_mfma_f32_16x16x32_bf16 v[74:77], v[166:169], v[220:223], v[74:77]
	v_mfma_f32_16x16x32_bf16 v[118:121], v[174:177], v[190:193], v[118:121]
	v_mfma_f32_16x16x32_bf16 v[114:117], v[182:185], v[190:193], v[114:117]
	v_mfma_f32_16x16x32_bf16 v[102:105], v[174:177], v[198:201], v[102:105]
	v_mfma_f32_16x16x32_bf16 v[98:101], v[182:185], v[198:201], v[98:101]
	v_mfma_f32_16x16x32_bf16 v[86:89], v[174:177], v[206:209], v[86:89]
	v_mfma_f32_16x16x32_bf16 v[82:85], v[182:185], v[206:209], v[82:85]
	v_mfma_f32_16x16x32_bf16 v[70:73], v[174:177], v[220:223], v[70:73]
	v_mfma_f32_16x16x32_bf16 v[66:69], v[182:185], v[220:223], v[66:69]
	s_setprio 0
	s_barrier
	s_add_i32 s76, s71, s49
	v_lshl_add_u64 v[214:215], s[42:43], 0, v[132:133]
	s_mov_b32 m0, s76
	ds_read_b128 v[186:189], v152 offset:16384
	ds_read_b128 v[190:193], v152 offset:17408
	ds_read_b128 v[194:197], v152 offset:18432
	ds_read_b128 v[198:201], v152 offset:19456
	ds_read_b128 v[202:205], v152 offset:20480
	ds_read_b128 v[206:209], v152 offset:21504
	ds_read_b128 v[210:213], v152 offset:22528
	ds_read_b128 v[220:223], v152 offset:23552
	s_add_u32 s84, s80, 0x0
	s_addc_u32 s85, s81, 0
	global_load_lds_dwordx4 v232, s[84:85]
	s_add_i32 m0, s76, 0x2000
	s_add_u32 s76, s42, 0x40000
	v_lshl_add_u64 v[224:225], s[42:43], 0, v[136:137]
	s_addc_u32 s77, s43, 0
	s_add_i32 s78, s72, s49
	s_add_u32 s84, s80, 0x100
	s_addc_u32 s85, s81, 0
	global_load_lds_dwordx4 v232, s[84:85]
	v_lshl_add_u64 v[226:227], s[76:77], 0, v[132:133]
	s_mov_b32 m0, s78
	v_lshl_add_u64 v[228:229], s[44:45], 0, v[134:135]
	s_add_u32 s84, s80, 0x8000
	s_addc_u32 s85, s81, 0
	global_load_lds_dwordx4 v232, s[84:85]
	v_lshl_add_u64 v[226:227], s[76:77], 0, v[136:137]
	s_add_i32 m0, s78, 0x2000
	s_nop 0
	s_add_u32 s84, s80, 0x8100
	s_addc_u32 s85, s81, 0
	global_load_lds_dwordx4 v232, s[84:85]
	v_lshl_add_u64 v[226:227], s[44:45], 0, v[130:131]
	s_mov_b32 m0, s17
	s_nop 0
	s_add_u32 s84, s80, 0x10000
	s_addc_u32 s85, s81, 0
	global_load_lds_dwordx4 v232, s[84:85]
	s_mov_b32 m0, s50
	s_nop 0
	s_add_u32 s84, s80, 0x10100
	s_addc_u32 s85, s81, 0
	global_load_lds_dwordx4 v232, s[84:85]
	s_waitcnt vmcnt(8)
	s_waitcnt lgkmcnt(0)
	s_setprio 1
	s_waitcnt lgkmcnt(0)
	v_mfma_f32_16x16x32_bf16 v[62:65], v[154:157], v[186:189], v[62:65]
	s_barrier
	v_mfma_f32_16x16x32_bf16 v[58:61], v[162:165], v[186:189], v[58:61]
	v_mfma_f32_16x16x32_bf16 v[46:49], v[154:157], v[194:197], v[46:49]
	v_mfma_f32_16x16x32_bf16 v[42:45], v[162:165], v[194:197], v[42:45]
	v_mfma_f32_16x16x32_bf16 v[30:33], v[154:157], v[202:205], v[30:33]
	v_mfma_f32_16x16x32_bf16 v[26:29], v[162:165], v[202:205], v[26:29]
	v_mfma_f32_16x16x32_bf16 v[14:17], v[154:157], v[210:213], v[14:17]
	v_mfma_f32_16x16x32_bf16 v[10:13], v[162:165], v[210:213], v[10:13]
	v_mfma_f32_16x16x32_bf16 v[54:57], v[170:173], v[186:189], v[54:57]
	v_mfma_f32_16x16x32_bf16 v[50:53], v[178:181], v[186:189], v[50:53]
	v_mfma_f32_16x16x32_bf16 v[38:41], v[170:173], v[194:197], v[38:41]
	v_mfma_f32_16x16x32_bf16 v[34:37], v[178:181], v[194:197], v[34:37]
	v_mfma_f32_16x16x32_bf16 v[22:25], v[170:173], v[202:205], v[22:25]
	v_mfma_f32_16x16x32_bf16 v[18:21], v[178:181], v[202:205], v[18:21]
	v_mfma_f32_16x16x32_bf16 v[6:9], v[170:173], v[210:213], v[6:9]
	v_mfma_f32_16x16x32_bf16 v[2:5], v[178:181], v[210:213], v[2:5]
	v_mfma_f32_16x16x32_bf16 v[62:65], v[158:161], v[190:193], v[62:65]
	v_mfma_f32_16x16x32_bf16 v[58:61], v[166:169], v[190:193], v[58:61]
	v_mfma_f32_16x16x32_bf16 v[46:49], v[158:161], v[198:201], v[46:49]
	v_mfma_f32_16x16x32_bf16 v[42:45], v[166:169], v[198:201], v[42:45]
	v_mfma_f32_16x16x32_bf16 v[30:33], v[158:161], v[206:209], v[30:33]
	v_mfma_f32_16x16x32_bf16 v[26:29], v[166:169], v[206:209], v[26:29]
	v_mfma_f32_16x16x32_bf16 v[14:17], v[158:161], v[220:223], v[14:17]
	v_mfma_f32_16x16x32_bf16 v[10:13], v[166:169], v[220:223], v[10:13]
	v_mfma_f32_16x16x32_bf16 v[54:57], v[174:177], v[190:193], v[54:57]
	v_mfma_f32_16x16x32_bf16 v[50:53], v[182:185], v[190:193], v[50:53]
	v_mfma_f32_16x16x32_bf16 v[38:41], v[174:177], v[198:201], v[38:41]
	v_mfma_f32_16x16x32_bf16 v[34:37], v[182:185], v[198:201], v[34:37]
	v_mfma_f32_16x16x32_bf16 v[22:25], v[174:177], v[206:209], v[22:25]
	v_mfma_f32_16x16x32_bf16 v[18:21], v[182:185], v[206:209], v[18:21]
	v_mfma_f32_16x16x32_bf16 v[6:9], v[174:177], v[220:223], v[6:9]
	v_mfma_f32_16x16x32_bf16 v[2:5], v[182:185], v[220:223], v[2:5]
	s_setprio 0
	s_barrier
	s_add_i32 s76, 0, 0x18000
	v_add_u32_e32 v153, s76, v151
	s_add_i32 s77, 0, 0x1c000
	ds_read_b128 v[154:157], v153
	ds_read_b128 v[158:161], v153 offset:1024
	ds_read_b128 v[162:165], v153 offset:2048
	ds_read_b128 v[166:169], v153 offset:3072
	v_add_u32_e32 v153, s77, v151
	ds_read_b128 v[170:173], v153
	ds_read_b128 v[174:177], v153 offset:1024
	ds_read_b128 v[178:181], v153 offset:2048
	ds_read_b128 v[182:185], v153 offset:3072
	s_add_u32 s44, s44, 0x40000
	s_addc_u32 s45, s45, 0
	s_mov_b32 m0, s51
	v_lshl_add_u64 v[230:231], s[44:45], 0, v[130:131]
	ds_read_b128 v[186:189], v152 offset:32768
	ds_read_b128 v[190:193], v152 offset:33792
	ds_read_b128 v[194:197], v152 offset:34816
	ds_read_b128 v[198:201], v152 offset:35840
	ds_read_b128 v[202:205], v152 offset:36864
	ds_read_b128 v[206:209], v152 offset:37888
	ds_read_b128 v[210:213], v152 offset:38912
	ds_read_b128 v[220:223], v152 offset:39936
	s_add_u32 s84, s80, 0x18000
	s_addc_u32 s85, s81, 0
	global_load_lds_dwordx4 v232, s[84:85]
	v_lshl_add_u64 v[230:231], s[44:45], 0, v[134:135]
	s_mov_b32 m0, s60
	s_nop 0
	s_add_u32 s84, s80, 0x18100
	s_addc_u32 s85, s81, 0
	global_load_lds_dwordx4 v232, s[84:85]
	s_waitcnt vmcnt(8)
	s_waitcnt lgkmcnt(0)
	s_setprio 1
	s_waitcnt lgkmcnt(0)
	v_mfma_f32_16x16x32_bf16 v[126:129], v[154:157], v[186:189], v[126:129]
	s_barrier
	v_mfma_f32_16x16x32_bf16 v[122:125], v[162:165], v[186:189], v[122:125]
	v_mfma_f32_16x16x32_bf16 v[110:113], v[154:157], v[194:197], v[110:113]
	v_mfma_f32_16x16x32_bf16 v[106:109], v[162:165], v[194:197], v[106:109]
	v_mfma_f32_16x16x32_bf16 v[94:97], v[154:157], v[202:205], v[94:97]
	v_mfma_f32_16x16x32_bf16 v[90:93], v[162:165], v[202:205], v[90:93]
	v_mfma_f32_16x16x32_bf16 v[78:81], v[154:157], v[210:213], v[78:81]
	v_mfma_f32_16x16x32_bf16 v[74:77], v[162:165], v[210:213], v[74:77]
	v_mfma_f32_16x16x32_bf16 v[118:121], v[170:173], v[186:189], v[118:121]
	v_mfma_f32_16x16x32_bf16 v[114:117], v[178:181], v[186:189], v[114:117]
	v_mfma_f32_16x16x32_bf16 v[102:105], v[170:173], v[194:197], v[102:105]
	v_mfma_f32_16x16x32_bf16 v[98:101], v[178:181], v[194:197], v[98:101]
	v_mfma_f32_16x16x32_bf16 v[86:89], v[170:173], v[202:205], v[86:89]
	v_mfma_f32_16x16x32_bf16 v[82:85], v[178:181], v[202:205], v[82:85]
	v_mfma_f32_16x16x32_bf16 v[70:73], v[170:173], v[210:213], v[70:73]
	v_mfma_f32_16x16x32_bf16 v[66:69], v[178:181], v[210:213], v[66:69]
	v_mfma_f32_16x16x32_bf16 v[126:129], v[158:161], v[190:193], v[126:129]
	v_mfma_f32_16x16x32_bf16 v[122:125], v[166:169], v[190:193], v[122:125]
	v_mfma_f32_16x16x32_bf16 v[110:113], v[158:161], v[198:201], v[110:113]
	v_mfma_f32_16x16x32_bf16 v[106:109], v[166:169], v[198:201], v[106:109]
	v_mfma_f32_16x16x32_bf16 v[94:97], v[158:161], v[206:209], v[94:97]
	v_mfma_f32_16x16x32_bf16 v[90:93], v[166:169], v[206:209], v[90:93]
	v_mfma_f32_16x16x32_bf16 v[78:81], v[158:161], v[220:223], v[78:81]
	v_mfma_f32_16x16x32_bf16 v[74:77], v[166:169], v[220:223], v[74:77]
	v_mfma_f32_16x16x32_bf16 v[118:121], v[174:177], v[190:193], v[118:121]
	v_mfma_f32_16x16x32_bf16 v[114:117], v[182:185], v[190:193], v[114:117]
	v_mfma_f32_16x16x32_bf16 v[102:105], v[174:177], v[198:201], v[102:105]
	v_mfma_f32_16x16x32_bf16 v[98:101], v[182:185], v[198:201], v[98:101]
	v_mfma_f32_16x16x32_bf16 v[86:89], v[174:177], v[206:209], v[86:89]
	v_mfma_f32_16x16x32_bf16 v[82:85], v[182:185], v[206:209], v[82:85]
	v_mfma_f32_16x16x32_bf16 v[70:73], v[174:177], v[220:223], v[70:73]
	v_mfma_f32_16x16x32_bf16 v[66:69], v[182:185], v[220:223], v[66:69]
	s_setprio 0
	s_barrier
	s_add_i32 s44, s76, s49
	v_lshl_add_u64 v[214:215], v[214:215], 0, s[12:13]
	s_mov_b32 m0, s44
	ds_read_b128 v[186:189], v152 offset:49152
	ds_read_b128 v[190:193], v152 offset:50176
	ds_read_b128 v[194:197], v152 offset:51200
	ds_read_b128 v[198:201], v152 offset:52224
	ds_read_b128 v[202:205], v152 offset:53248
	ds_read_b128 v[206:209], v152 offset:54272
	ds_read_b128 v[210:213], v152 offset:55296
	ds_read_b128 v[220:223], v152 offset:56320
	s_add_u32 s84, s80, 0x40000
	s_addc_u32 s85, s81, 0
	global_load_lds_dwordx4 v232, s[84:85]
	s_add_i32 m0, s44, 0x2000
	s_add_u32 s42, s42, 0x40080
	v_lshl_add_u64 v[214:215], v[224:225], 0, s[12:13]
	s_addc_u32 s43, s43, 0
	s_add_i32 s44, s77, s49
	s_add_u32 s84, s80, 0x40100
	s_addc_u32 s85, s81, 0
	global_load_lds_dwordx4 v232, s[84:85]
	v_lshl_add_u64 v[214:215], s[42:43], 0, v[132:133]
	s_mov_b32 m0, s44
	s_nop 0
	s_add_u32 s84, s80, 0x48000
	s_addc_u32 s85, s81, 0
	global_load_lds_dwordx4 v232, s[84:85]
	v_lshl_add_u64 v[214:215], s[42:43], 0, v[136:137]
	s_add_i32 m0, s44, 0x2000
	s_nop 0
	s_add_u32 s84, s80, 0x48100
	s_addc_u32 s85, s81, 0
	global_load_lds_dwordx4 v232, s[84:85]
	v_lshl_add_u64 v[214:215], v[226:227], 0, s[12:13]
	s_mov_b32 m0, s68
	s_nop 0
	s_add_u32 s84, s80, 0x50000
	s_addc_u32 s85, s81, 0
	global_load_lds_dwordx4 v232, s[84:85]
	v_lshl_add_u64 v[214:215], v[228:229], 0, s[12:13]
	s_mov_b32 m0, s69
	s_nop 0
	s_add_u32 s84, s80, 0x50100
	s_addc_u32 s85, s81, 0
	global_load_lds_dwordx4 v232, s[84:85]
	s_waitcnt vmcnt(8)
	s_waitcnt lgkmcnt(0)
	s_setprio 1
	s_waitcnt lgkmcnt(0)
	v_mfma_f32_16x16x32_bf16 v[62:65], v[154:157], v[186:189], v[62:65]
	s_barrier
	v_mfma_f32_16x16x32_bf16 v[58:61], v[162:165], v[186:189], v[58:61]
	v_mfma_f32_16x16x32_bf16 v[46:49], v[154:157], v[194:197], v[46:49]
	v_mfma_f32_16x16x32_bf16 v[42:45], v[162:165], v[194:197], v[42:45]
	v_mfma_f32_16x16x32_bf16 v[30:33], v[154:157], v[202:205], v[30:33]
	v_mfma_f32_16x16x32_bf16 v[26:29], v[162:165], v[202:205], v[26:29]
	v_mfma_f32_16x16x32_bf16 v[14:17], v[154:157], v[210:213], v[14:17]
	v_mfma_f32_16x16x32_bf16 v[10:13], v[162:165], v[210:213], v[10:13]
	v_mfma_f32_16x16x32_bf16 v[54:57], v[170:173], v[186:189], v[54:57]
	v_mfma_f32_16x16x32_bf16 v[50:53], v[178:181], v[186:189], v[50:53]
	v_mfma_f32_16x16x32_bf16 v[38:41], v[170:173], v[194:197], v[38:41]
	v_mfma_f32_16x16x32_bf16 v[34:37], v[178:181], v[194:197], v[34:37]
	v_mfma_f32_16x16x32_bf16 v[22:25], v[170:173], v[202:205], v[22:25]
	v_mfma_f32_16x16x32_bf16 v[18:21], v[178:181], v[202:205], v[18:21]
	v_mfma_f32_16x16x32_bf16 v[6:9], v[170:173], v[210:213], v[6:9]
	v_mfma_f32_16x16x32_bf16 v[2:5], v[178:181], v[210:213], v[2:5]
	v_mfma_f32_16x16x32_bf16 v[62:65], v[158:161], v[190:193], v[62:65]
	v_mfma_f32_16x16x32_bf16 v[58:61], v[166:169], v[190:193], v[58:61]
	v_mfma_f32_16x16x32_bf16 v[46:49], v[158:161], v[198:201], v[46:49]
	v_mfma_f32_16x16x32_bf16 v[42:45], v[166:169], v[198:201], v[42:45]
	v_mfma_f32_16x16x32_bf16 v[30:33], v[158:161], v[206:209], v[30:33]
	v_mfma_f32_16x16x32_bf16 v[26:29], v[166:169], v[206:209], v[26:29]
	v_mfma_f32_16x16x32_bf16 v[14:17], v[158:161], v[220:223], v[14:17]
	v_mfma_f32_16x16x32_bf16 v[10:13], v[166:169], v[220:223], v[10:13]
	v_mfma_f32_16x16x32_bf16 v[54:57], v[174:177], v[190:193], v[54:57]
	v_mfma_f32_16x16x32_bf16 v[50:53], v[182:185], v[190:193], v[50:53]
	v_mfma_f32_16x16x32_bf16 v[38:41], v[174:177], v[198:201], v[38:41]
	v_mfma_f32_16x16x32_bf16 v[34:37], v[182:185], v[198:201], v[34:37]
	v_mfma_f32_16x16x32_bf16 v[22:25], v[174:177], v[206:209], v[22:25]
	v_mfma_f32_16x16x32_bf16 v[18:21], v[182:185], v[206:209], v[18:21]
	v_mfma_f32_16x16x32_bf16 v[6:9], v[174:177], v[220:223], v[6:9]
	v_mfma_f32_16x16x32_bf16 v[2:5], v[182:185], v[220:223], v[2:5]
	s_setprio 0
	s_barrier
	s_add_i32 s75, s75, 2
	s_add_u32 s40, s40, 0x100
	s_addc_u32 s41, s41, 0
	s_add_u32 s40, s0, 0xffffff00
	s_addc_u32 s41, s29, -1
	s_andn2_b64 vcc, exec, s[8:9]
	s_cbranch_vccnz .LBB0_570
	v_mov_b32_e32 v2, 0
	s_mov_b32 s16, s18
	s_mov_b32 s14, s20
	s_mov_b64 s[10:11], s[36:37]
	s_mov_b32 s70, s28
	v_mov_b32_e32 v3, v2
	v_mov_b32_e32 v4, v2
	v_mov_b32_e32 v5, v2
	v_mov_b32_e32 v6, v2
	v_mov_b32_e32 v7, v2
	v_mov_b32_e32 v8, v2
	v_mov_b32_e32 v9, v2
	v_mov_b32_e32 v18, v2
	v_mov_b32_e32 v19, v2
	v_mov_b32_e32 v20, v2
	v_mov_b32_e32 v21, v2
	v_mov_b32_e32 v22, v2
	v_mov_b32_e32 v23, v2
	v_mov_b32_e32 v24, v2
	v_mov_b32_e32 v25, v2
	v_mov_b32_e32 v34, v2
	v_mov_b32_e32 v35, v2
	v_mov_b32_e32 v36, v2
	v_mov_b32_e32 v37, v2
	v_mov_b32_e32 v38, v2
	v_mov_b32_e32 v39, v2
	v_mov_b32_e32 v40, v2
	v_mov_b32_e32 v41, v2
	v_mov_b32_e32 v50, v2
	v_mov_b32_e32 v51, v2
	v_mov_b32_e32 v52, v2
	v_mov_b32_e32 v53, v2
	v_mov_b32_e32 v54, v2
	v_mov_b32_e32 v55, v2
	v_mov_b32_e32 v56, v2
	v_mov_b32_e32 v57, v2
	v_mov_b32_e32 v10, v2
	v_mov_b32_e32 v11, v2
	v_mov_b32_e32 v12, v2
	v_mov_b32_e32 v13, v2
	v_mov_b32_e32 v14, v2
	v_mov_b32_e32 v15, v2
	v_mov_b32_e32 v16, v2
	v_mov_b32_e32 v17, v2
	v_mov_b32_e32 v26, v2
	v_mov_b32_e32 v27, v2
	v_mov_b32_e32 v28, v2
	v_mov_b32_e32 v29, v2
	v_mov_b32_e32 v30, v2
	v_mov_b32_e32 v31, v2
	v_mov_b32_e32 v32, v2
	v_mov_b32_e32 v33, v2
	v_mov_b32_e32 v42, v2
	v_mov_b32_e32 v43, v2
	v_mov_b32_e32 v44, v2
	v_mov_b32_e32 v45, v2
	v_mov_b32_e32 v46, v2
	v_mov_b32_e32 v47, v2
	v_mov_b32_e32 v48, v2
	v_mov_b32_e32 v49, v2
	v_mov_b32_e32 v58, v2
	v_mov_b32_e32 v59, v2
	v_mov_b32_e32 v60, v2
	v_mov_b32_e32 v61, v2
	v_mov_b32_e32 v62, v2
	v_mov_b32_e32 v63, v2
	v_mov_b32_e32 v64, v2
	v_mov_b32_e32 v65, v2
	v_mov_b32_e32 v66, v2
	v_mov_b32_e32 v67, v2
	v_mov_b32_e32 v68, v2
	v_mov_b32_e32 v69, v2
	v_mov_b32_e32 v70, v2
	v_mov_b32_e32 v71, v2
	v_mov_b32_e32 v72, v2
	v_mov_b32_e32 v73, v2
	v_mov_b32_e32 v82, v2
	v_mov_b32_e32 v83, v2
	v_mov_b32_e32 v84, v2
	v_mov_b32_e32 v85, v2
	v_mov_b32_e32 v86, v2
	v_mov_b32_e32 v87, v2
	v_mov_b32_e32 v88, v2
	v_mov_b32_e32 v89, v2
	v_mov_b32_e32 v98, v2
	v_mov_b32_e32 v99, v2
	v_mov_b32_e32 v100, v2
	v_mov_b32_e32 v101, v2
	v_mov_b32_e32 v102, v2
	v_mov_b32_e32 v103, v2
	v_mov_b32_e32 v104, v2
	v_mov_b32_e32 v105, v2
	v_mov_b32_e32 v114, v2
	v_mov_b32_e32 v115, v2
	v_mov_b32_e32 v116, v2
	v_mov_b32_e32 v117, v2
	v_mov_b32_e32 v118, v2
	v_mov_b32_e32 v119, v2
	v_mov_b32_e32 v120, v2
	v_mov_b32_e32 v121, v2
	v_mov_b32_e32 v74, v2
	v_mov_b32_e32 v75, v2
	v_mov_b32_e32 v76, v2
	v_mov_b32_e32 v77, v2
	v_mov_b32_e32 v78, v2
	v_mov_b32_e32 v79, v2
	v_mov_b32_e32 v80, v2
	v_mov_b32_e32 v81, v2
	v_mov_b32_e32 v90, v2
	v_mov_b32_e32 v91, v2
	v_mov_b32_e32 v92, v2
	v_mov_b32_e32 v93, v2
	v_mov_b32_e32 v94, v2
	v_mov_b32_e32 v95, v2
	v_mov_b32_e32 v96, v2
	v_mov_b32_e32 v97, v2
	v_mov_b32_e32 v106, v2
	v_mov_b32_e32 v107, v2
	v_mov_b32_e32 v108, v2
	v_mov_b32_e32 v109, v2
	v_mov_b32_e32 v110, v2
	v_mov_b32_e32 v111, v2
	v_mov_b32_e32 v112, v2
	v_mov_b32_e32 v113, v2
	v_mov_b32_e32 v122, v2
	v_mov_b32_e32 v123, v2
	v_mov_b32_e32 v124, v2
	v_mov_b32_e32 v125, v2
	v_mov_b32_e32 v126, v2
	v_mov_b32_e32 v127, v2
	v_mov_b32_e32 v128, v2
	v_mov_b32_e32 v129, v2
	s_andn2_b64 vcc, exec, s[6:7]
	s_cbranch_vccnz .LBB0_571
	s_branch .LBB0_572

.LBB0_574:
	s_lshl_b32 s0, s15, 5
	s_lshl_b32 s6, s16, 8
	s_or_b32 s0, s6, s0
	s_lshl_b32 s40, s14, 8
	v_and_or_b32 v210, v150, 24, s0
	s_add_i32 s0, s40, s61
	v_or_b32_e32 v130, s0, v219
	v_ashrrev_i32_e32 v211, 31, v210
	v_ashrrev_i32_e32 v131, 31, v130
	v_lshl_add_u64 v[132:133], v[210:211], 1, s[38:39]
	v_lshlrev_b64 v[134:135], 11, v[130:131]
	v_lshl_add_u64 v[134:135], v[132:133], 0, v[134:135]
	s_barrier
	v_lshlrev_b32_e32 v234, 4, v1
	v_add_u32_e32 v234, s49, v234
	v_add_u32_e32 v235, 0x10000, v234
	ds_read_b128 v[194:197], v235 offset:0
	ds_read_b128 v[186:189], v235 offset:8192
	v_or_b32_e32 v134, 16, v130
	v_ashrrev_i32_e32 v135, 31, v134
	v_lshlrev_b64 v[134:135], 11, v[134:135]
	v_lshl_add_u64 v[134:135], v[132:133], 0, v[134:135]
	ds_read_b128 v[182:185], v235 offset:16384
	ds_read_b128 v[178:181], v235 offset:24576
	v_or_b32_e32 v134, 32, v130
	v_ashrrev_i32_e32 v135, 31, v134
	v_lshlrev_b64 v[134:135], 11, v[134:135]
	v_lshl_add_u64 v[134:135], v[132:133], 0, v[134:135]
	ds_read_b128 v[174:177], v234 offset:0
	ds_read_b128 v[170:173], v234 offset:8192
	v_or_b32_e32 v134, 48, v130
	v_ashrrev_i32_e32 v135, 31, v134
	v_lshlrev_b64 v[134:135], 11, v[134:135]
	v_lshl_add_u64 v[134:135], v[132:133], 0, v[134:135]
	ds_read_b128 v[166:169], v234 offset:16384
	ds_read_b128 v[162:165], v234 offset:24576
	v_add_u32_e32 v134, 0x80, v130
	v_ashrrev_i32_e32 v135, 31, v134
	v_lshlrev_b64 v[134:135], 11, v[134:135]
	v_lshl_add_u64 v[134:135], v[132:133], 0, v[134:135]
	ds_read_b128 v[158:161], v235 offset:32768
	ds_read_b128 v[154:157], v235 offset:40960
	v_add_u32_e32 v134, 0x90, v130
	v_ashrrev_i32_e32 v135, 31, v134
	v_lshlrev_b64 v[134:135], 11, v[134:135]
	v_lshl_add_u64 v[134:135], v[132:133], 0, v[134:135]
	ds_read_b128 v[150:153], v235 offset:49152
	ds_read_b128 v[146:149], v235 offset:57344
	v_add_u32_e32 v134, 0xa0, v130
	v_add_u32_e32 v130, 0xb0, v130
	v_ashrrev_i32_e32 v135, 31, v134
	v_ashrrev_i32_e32 v131, 31, v130
	v_lshlrev_b64 v[134:135], 11, v[134:135]
	v_lshlrev_b64 v[130:131], 11, v[130:131]
	v_lshl_add_u64 v[134:135], v[132:133], 0, v[134:135]
	v_lshl_add_u64 v[130:131], v[132:133], 0, v[130:131]
	ds_read_b128 v[142:145], v234 offset:32768
	ds_read_b128 v[138:141], v234 offset:40960
	s_nop 0
	global_load_dwordx4 v[134:137], v[130:131], off
	s_nop 0
	global_load_dwordx4 v[130:133], v[130:131], off offset:256
	s_waitcnt lgkmcnt(0)
	s_barrier
	v_mbcnt_lo_u32_b32 v190, -1, 0
	v_mbcnt_hi_u32_b32 v190, -1, v190
	v_and_b32_e32 v192, 64, v190
	v_xor_b32_e32 v191, 16, v190
	v_add_u32_e32 v192, 64, v192
	v_cmp_lt_i32_e32 vcc, v191, v192
	v_mul_f32_e32 v193, v129, v129
	v_fmac_f32_e32 v193, v128, v128
	v_cndmask_b32_e32 v191, v190, v191, vcc
	v_lshlrev_b32_e32 v220, 2, v191
	v_mul_f32_e32 v191, v127, v127
	v_fmac_f32_e32 v191, v126, v126
	v_add_f32_e32 v191, v191, v193
	v_mul_f32_e32 v193, v123, v123
	v_mul_f32_e32 v198, v125, v125
	v_fmac_f32_e32 v193, v122, v122
	v_fmac_f32_e32 v198, v124, v124
	v_add_f32_e32 v193, v193, v198
	v_add_f32_e32 v191, v193, v191
	v_mul_f32_e32 v193, v119, v119
	v_mul_f32_e32 v198, v121, v121
	v_fmac_f32_e32 v193, v118, v118
	v_fmac_f32_e32 v198, v120, v120
	v_add_f32_e32 v193, v193, v198
	v_add_f32_e32 v191, v193, v191
	v_mul_f32_e32 v193, v115, v115
	v_mul_f32_e32 v198, v117, v117
	v_fmac_f32_e32 v193, v114, v114
	v_fmac_f32_e32 v198, v116, v116
	v_add_f32_e32 v193, v193, v198
	v_add_f32_e32 v191, v193, v191
	ds_bpermute_b32 v193, v220, v191
	v_xor_b32_e32 v198, 32, v190
	v_cmp_lt_i32_e32 vcc, v198, v192
	s_lshl_b32 s0, s15, 2
	v_cmp_gt_u32_e64 s[6:7], 16, v1
	v_cndmask_b32_e32 v190, v190, v198, vcc
	v_lshlrev_b32_e32 v221, 2, v190
	s_waitcnt lgkmcnt(0)
	v_add_f32_e32 v190, v191, v193
	ds_bpermute_b32 v191, v221, v190
	s_add_i32 s15, s0, 0
	s_and_saveexec_b64 s[8:9], s[6:7]
	s_cbranch_execz .LBB0_576
	s_lshl_b32 s0, s1, 10
	s_add_i32 s0, s15, s0
	v_lshl_add_u32 v192, v219, 4, s0
	s_waitcnt lgkmcnt(0)
	v_add_f32_e32 v190, v190, v191
	ds_write_b32 v192, v190

.LBB0_874:
	v_add_u32_e32 v164, s44, v150
	v_add_u32_e32 v180, s45, v150
	s_add_u32 s24, s12, s20
	ds_read_b128 v[152:155], v164
	ds_read_b128 v[156:159], v164 offset:1024
	ds_read_b128 v[160:163], v164 offset:2048
	ds_read_b128 v[164:167], v164 offset:3072
	ds_read_b128 v[168:171], v180
	ds_read_b128 v[172:175], v180 offset:1024
	ds_read_b128 v[176:179], v180 offset:2048
	ds_read_b128 v[180:183], v180 offset:3072
	s_addc_u32 s25, s13, s21
	s_add_u32 s24, s24, 0x100
	s_addc_u32 s25, s25, 0
	s_add_u32 s50, s17, s20
	s_addc_u32 s51, s48, s21
	s_cmpk_eq_i32 s20, 0x1500
	s_cselect_b32 s27, s19, s25
	s_cselect_b32 s26, s18, s24
	s_cselect_b32 s25, s7, s51
	s_cselect_b32 s24, s6, s50
	v_lshl_add_u64 v[208:209], v[146:147], 0, s[20:21]
	s_add_i32 m0, s37, 0xc000
	ds_read_b128 v[184:187], v151
	ds_read_b128 v[188:191], v151 offset:1024
	ds_read_b128 v[192:195], v151 offset:2048
	ds_read_b128 v[196:199], v151 offset:3072
	ds_read_b128 v[200:203], v151 offset:4096
	ds_read_b128 v[204:207], v151 offset:5120
	ds_read_b128 v[214:217], v151 offset:6144
	ds_read_b128 v[218:221], v151 offset:7168
	global_load_lds_dwordx4 v[208:209], off
	v_lshl_add_u64 v[208:209], v[148:149], 0, s[20:21]
	s_add_i32 m0, s37, 0xe000
	s_nop 0
	global_load_lds_dwordx4 v[208:209], off
	s_waitcnt vmcnt(8)
	s_waitcnt lgkmcnt(0)
	s_setprio 1
	s_waitcnt lgkmcnt(0)
	v_mfma_f32_16x16x32_bf16 v[126:129], v[152:155], v[184:187], v[126:129]
	s_barrier
	v_mfma_f32_16x16x32_bf16 v[122:125], v[160:163], v[184:187], v[122:125]
	v_mfma_f32_16x16x32_bf16 v[110:113], v[152:155], v[192:195], v[110:113]
	v_mfma_f32_16x16x32_bf16 v[106:109], v[160:163], v[192:195], v[106:109]
	v_mfma_f32_16x16x32_bf16 v[94:97], v[152:155], v[200:203], v[94:97]
	v_mfma_f32_16x16x32_bf16 v[90:93], v[160:163], v[200:203], v[90:93]
	v_mfma_f32_16x16x32_bf16 v[78:81], v[152:155], v[214:217], v[78:81]
	v_mfma_f32_16x16x32_bf16 v[74:77], v[160:163], v[214:217], v[74:77]
	v_mfma_f32_16x16x32_bf16 v[118:121], v[168:171], v[184:187], v[118:121]
	v_mfma_f32_16x16x32_bf16 v[114:117], v[176:179], v[184:187], v[114:117]
	v_mfma_f32_16x16x32_bf16 v[102:105], v[168:171], v[192:195], v[102:105]
	v_mfma_f32_16x16x32_bf16 v[98:101], v[176:179], v[192:195], v[98:101]
	v_mfma_f32_16x16x32_bf16 v[86:89], v[168:171], v[200:203], v[86:89]
	v_mfma_f32_16x16x32_bf16 v[82:85], v[176:179], v[200:203], v[82:85]
	v_mfma_f32_16x16x32_bf16 v[70:73], v[168:171], v[214:217], v[70:73]
	v_mfma_f32_16x16x32_bf16 v[66:69], v[176:179], v[214:217], v[66:69]
	v_mfma_f32_16x16x32_bf16 v[126:129], v[156:159], v[188:191], v[126:129]
	v_mfma_f32_16x16x32_bf16 v[122:125], v[164:167], v[188:191], v[122:125]
	v_mfma_f32_16x16x32_bf16 v[110:113], v[156:159], v[196:199], v[110:113]
	v_mfma_f32_16x16x32_bf16 v[106:109], v[164:167], v[196:199], v[106:109]
	v_mfma_f32_16x16x32_bf16 v[94:97], v[156:159], v[204:207], v[94:97]
	v_mfma_f32_16x16x32_bf16 v[90:93], v[164:167], v[204:207], v[90:93]
	v_mfma_f32_16x16x32_bf16 v[78:81], v[156:159], v[218:221], v[78:81]
	v_mfma_f32_16x16x32_bf16 v[74:77], v[164:167], v[218:221], v[74:77]
	v_mfma_f32_16x16x32_bf16 v[118:121], v[172:175], v[188:191], v[118:121]
	v_mfma_f32_16x16x32_bf16 v[114:117], v[180:183], v[188:191], v[114:117]
	v_mfma_f32_16x16x32_bf16 v[102:105], v[172:175], v[196:199], v[102:105]
	v_mfma_f32_16x16x32_bf16 v[98:101], v[180:183], v[196:199], v[98:101]
	v_mfma_f32_16x16x32_bf16 v[86:89], v[172:175], v[204:207], v[86:89]
	v_mfma_f32_16x16x32_bf16 v[82:85], v[180:183], v[204:207], v[82:85]
	v_mfma_f32_16x16x32_bf16 v[70:73], v[172:175], v[218:221], v[70:73]
	v_mfma_f32_16x16x32_bf16 v[66:69], v[180:183], v[218:221], v[66:69]
	s_setprio 0
	s_barrier
	s_add_i32 s50, s44, s36
	v_lshl_add_u64 v[208:209], s[24:25], 0, v[132:133]
	s_mov_b32 m0, s50
	ds_read_b128 v[184:187], v151 offset:16384
	ds_read_b128 v[188:191], v151 offset:17408
	ds_read_b128 v[192:195], v151 offset:18432
	ds_read_b128 v[196:199], v151 offset:19456
	ds_read_b128 v[200:203], v151 offset:20480
	ds_read_b128 v[204:207], v151 offset:21504
	ds_read_b128 v[214:217], v151 offset:22528
	ds_read_b128 v[218:221], v151 offset:23552
	global_load_lds_dwordx4 v[208:209], off
	s_add_i32 m0, s50, 0x2000
	s_add_u32 s50, s24, 0xb0000
	v_lshl_add_u64 v[222:223], s[24:25], 0, v[136:137]
	s_addc_u32 s51, s25, 0
	s_add_i32 s56, s45, s36
	global_load_lds_dwordx4 v[222:223], off
	v_lshl_add_u64 v[224:225], s[50:51], 0, v[132:133]
	s_mov_b32 m0, s56
	v_lshl_add_u64 v[226:227], s[26:27], 0, v[134:135]
	global_load_lds_dwordx4 v[224:225], off
	v_lshl_add_u64 v[224:225], s[50:51], 0, v[136:137]
	s_add_i32 m0, s56, 0x2000
	s_nop 0
	global_load_lds_dwordx4 v[224:225], off
	v_lshl_add_u64 v[224:225], s[26:27], 0, v[130:131]
	s_mov_b32 m0, s37
	s_nop 0
	global_load_lds_dwordx4 v[224:225], off
	s_mov_b32 m0, s38
	s_nop 0
	global_load_lds_dwordx4 v[226:227], off
	s_waitcnt vmcnt(8)
	s_waitcnt lgkmcnt(0)
	s_setprio 1
	s_waitcnt lgkmcnt(0)
	v_mfma_f32_16x16x32_bf16 v[62:65], v[152:155], v[184:187], v[62:65]
	s_barrier
	v_mfma_f32_16x16x32_bf16 v[58:61], v[160:163], v[184:187], v[58:61]
	v_mfma_f32_16x16x32_bf16 v[46:49], v[152:155], v[192:195], v[46:49]
	v_mfma_f32_16x16x32_bf16 v[42:45], v[160:163], v[192:195], v[42:45]
	v_mfma_f32_16x16x32_bf16 v[30:33], v[152:155], v[200:203], v[30:33]
	v_mfma_f32_16x16x32_bf16 v[26:29], v[160:163], v[200:203], v[26:29]
	v_mfma_f32_16x16x32_bf16 v[14:17], v[152:155], v[214:217], v[14:17]
	v_mfma_f32_16x16x32_bf16 v[10:13], v[160:163], v[214:217], v[10:13]
	v_mfma_f32_16x16x32_bf16 v[54:57], v[168:171], v[184:187], v[54:57]
	v_mfma_f32_16x16x32_bf16 v[50:53], v[176:179], v[184:187], v[50:53]
	v_mfma_f32_16x16x32_bf16 v[38:41], v[168:171], v[192:195], v[38:41]
	v_mfma_f32_16x16x32_bf16 v[34:37], v[176:179], v[192:195], v[34:37]
	v_mfma_f32_16x16x32_bf16 v[22:25], v[168:171], v[200:203], v[22:25]
	v_mfma_f32_16x16x32_bf16 v[18:21], v[176:179], v[200:203], v[18:21]
	v_mfma_f32_16x16x32_bf16 v[6:9], v[168:171], v[214:217], v[6:9]
	v_mfma_f32_16x16x32_bf16 v[2:5], v[176:179], v[214:217], v[2:5]
	v_mfma_f32_16x16x32_bf16 v[62:65], v[156:159], v[188:191], v[62:65]
	v_mfma_f32_16x16x32_bf16 v[58:61], v[164:167], v[188:191], v[58:61]
	v_mfma_f32_16x16x32_bf16 v[46:49], v[156:159], v[196:199], v[46:49]
	v_mfma_f32_16x16x32_bf16 v[42:45], v[164:167], v[196:199], v[42:45]
	v_mfma_f32_16x16x32_bf16 v[30:33], v[156:159], v[204:207], v[30:33]
	v_mfma_f32_16x16x32_bf16 v[26:29], v[164:167], v[204:207], v[26:29]
	v_mfma_f32_16x16x32_bf16 v[14:17], v[156:159], v[218:221], v[14:17]
	v_mfma_f32_16x16x32_bf16 v[10:13], v[164:167], v[218:221], v[10:13]
	v_mfma_f32_16x16x32_bf16 v[54:57], v[172:175], v[188:191], v[54:57]
	v_mfma_f32_16x16x32_bf16 v[50:53], v[180:183], v[188:191], v[50:53]
	v_mfma_f32_16x16x32_bf16 v[38:41], v[172:175], v[196:199], v[38:41]
	v_mfma_f32_16x16x32_bf16 v[34:37], v[180:183], v[196:199], v[34:37]
	v_mfma_f32_16x16x32_bf16 v[22:25], v[172:175], v[204:207], v[22:25]
	v_mfma_f32_16x16x32_bf16 v[18:21], v[180:183], v[204:207], v[18:21]
	v_mfma_f32_16x16x32_bf16 v[6:9], v[172:175], v[218:221], v[6:9]
	v_mfma_f32_16x16x32_bf16 v[2:5], v[180:183], v[218:221], v[2:5]
	s_setprio 0
	s_barrier
	s_add_i32 s50, 0, 0x18000
	s_add_i32 s51, 0, 0x1c000
	v_add_u32_e32 v164, s50, v150
	v_add_u32_e32 v180, s51, v150
	ds_read_b128 v[152:155], v164
	ds_read_b128 v[156:159], v164 offset:1024
	ds_read_b128 v[160:163], v164 offset:2048
	ds_read_b128 v[164:167], v164 offset:3072
	ds_read_b128 v[168:171], v180
	ds_read_b128 v[172:175], v180 offset:1024
	ds_read_b128 v[176:179], v180 offset:2048
	ds_read_b128 v[180:183], v180 offset:3072
	s_add_u32 s26, s26, 0xb0000
	s_addc_u32 s27, s27, 0
	s_mov_b32 m0, s39
	v_lshl_add_u64 v[228:229], s[26:27], 0, v[130:131]
	ds_read_b128 v[184:187], v151 offset:32768
	ds_read_b128 v[188:191], v151 offset:33792
	ds_read_b128 v[192:195], v151 offset:34816
	ds_read_b128 v[196:199], v151 offset:35840
	ds_read_b128 v[200:203], v151 offset:36864
	ds_read_b128 v[204:207], v151 offset:37888
	ds_read_b128 v[214:217], v151 offset:38912
	ds_read_b128 v[218:221], v151 offset:39936
	global_load_lds_dwordx4 v[228:229], off
	v_lshl_add_u64 v[228:229], s[26:27], 0, v[134:135]
	s_mov_b32 m0, s40
	s_nop 0
	global_load_lds_dwordx4 v[228:229], off
	s_waitcnt vmcnt(8)
	s_waitcnt lgkmcnt(0)
	s_setprio 1
	s_waitcnt lgkmcnt(0)
	v_mfma_f32_16x16x32_bf16 v[126:129], v[152:155], v[184:187], v[126:129]
	s_barrier
	v_mfma_f32_16x16x32_bf16 v[122:125], v[160:163], v[184:187], v[122:125]
	v_mfma_f32_16x16x32_bf16 v[110:113], v[152:155], v[192:195], v[110:113]
	v_mfma_f32_16x16x32_bf16 v[106:109], v[160:163], v[192:195], v[106:109]
	v_mfma_f32_16x16x32_bf16 v[94:97], v[152:155], v[200:203], v[94:97]
	v_mfma_f32_16x16x32_bf16 v[90:93], v[160:163], v[200:203], v[90:93]
	v_mfma_f32_16x16x32_bf16 v[78:81], v[152:155], v[214:217], v[78:81]
	v_mfma_f32_16x16x32_bf16 v[74:77], v[160:163], v[214:217], v[74:77]
	v_mfma_f32_16x16x32_bf16 v[118:121], v[168:171], v[184:187], v[118:121]
	v_mfma_f32_16x16x32_bf16 v[114:117], v[176:179], v[184:187], v[114:117]
	v_mfma_f32_16x16x32_bf16 v[102:105], v[168:171], v[192:195], v[102:105]
	v_mfma_f32_16x16x32_bf16 v[98:101], v[176:179], v[192:195], v[98:101]
	v_mfma_f32_16x16x32_bf16 v[86:89], v[168:171], v[200:203], v[86:89]
	v_mfma_f32_16x16x32_bf16 v[82:85], v[176:179], v[200:203], v[82:85]
	v_mfma_f32_16x16x32_bf16 v[70:73], v[168:171], v[214:217], v[70:73]
	v_mfma_f32_16x16x32_bf16 v[66:69], v[176:179], v[214:217], v[66:69]
	v_mfma_f32_16x16x32_bf16 v[126:129], v[156:159], v[188:191], v[126:129]
	v_mfma_f32_16x16x32_bf16 v[122:125], v[164:167], v[188:191], v[122:125]
	v_mfma_f32_16x16x32_bf16 v[110:113], v[156:159], v[196:199], v[110:113]
	v_mfma_f32_16x16x32_bf16 v[106:109], v[164:167], v[196:199], v[106:109]
	v_mfma_f32_16x16x32_bf16 v[94:97], v[156:159], v[204:207], v[94:97]
	v_mfma_f32_16x16x32_bf16 v[90:93], v[164:167], v[204:207], v[90:93]
	v_mfma_f32_16x16x32_bf16 v[78:81], v[156:159], v[218:221], v[78:81]
	v_mfma_f32_16x16x32_bf16 v[74:77], v[164:167], v[218:221], v[74:77]
	v_mfma_f32_16x16x32_bf16 v[118:121], v[172:175], v[188:191], v[118:121]
	v_mfma_f32_16x16x32_bf16 v[114:117], v[180:183], v[188:191], v[114:117]
	v_mfma_f32_16x16x32_bf16 v[102:105], v[172:175], v[196:199], v[102:105]
	v_mfma_f32_16x16x32_bf16 v[98:101], v[180:183], v[196:199], v[98:101]
	v_mfma_f32_16x16x32_bf16 v[86:89], v[172:175], v[204:207], v[86:89]
	v_mfma_f32_16x16x32_bf16 v[82:85], v[180:183], v[204:207], v[82:85]
	v_mfma_f32_16x16x32_bf16 v[70:73], v[172:175], v[218:221], v[70:73]
	v_mfma_f32_16x16x32_bf16 v[66:69], v[180:183], v[218:221], v[66:69]
	s_setprio 0
	s_barrier
	s_add_i32 s26, s50, s36
	v_lshl_add_u64 v[208:209], v[208:209], 0, s[14:15]
	s_mov_b32 m0, s26
	ds_read_b128 v[184:187], v151 offset:49152
	ds_read_b128 v[188:191], v151 offset:50176
	ds_read_b128 v[192:195], v151 offset:51200
	ds_read_b128 v[196:199], v151 offset:52224
	ds_read_b128 v[200:203], v151 offset:53248
	ds_read_b128 v[204:207], v151 offset:54272
	ds_read_b128 v[214:217], v151 offset:55296
	ds_read_b128 v[218:221], v151 offset:56320
	global_load_lds_dwordx4 v[208:209], off
	s_add_i32 m0, s26, 0x2000
	s_add_u32 s24, s24, 0xb0080
	v_lshl_add_u64 v[208:209], v[222:223], 0, s[14:15]
	s_addc_u32 s25, s25, 0
	s_add_i32 s26, s51, s36
	global_load_lds_dwordx4 v[208:209], off
	v_lshl_add_u64 v[208:209], s[24:25], 0, v[132:133]
	s_mov_b32 m0, s26
	s_nop 0
	global_load_lds_dwordx4 v[208:209], off
	v_lshl_add_u64 v[208:209], s[24:25], 0, v[136:137]
	s_add_i32 m0, s26, 0x2000
	s_nop 0
	global_load_lds_dwordx4 v[208:209], off
	v_lshl_add_u64 v[208:209], v[224:225], 0, s[14:15]
	s_mov_b32 m0, s41
	s_nop 0
	global_load_lds_dwordx4 v[208:209], off
	v_lshl_add_u64 v[208:209], v[226:227], 0, s[14:15]
	s_mov_b32 m0, s42
	s_nop 0
	global_load_lds_dwordx4 v[208:209], off
	s_waitcnt vmcnt(8)
	s_waitcnt lgkmcnt(0)
	s_setprio 1
	s_waitcnt lgkmcnt(0)
	v_mfma_f32_16x16x32_bf16 v[62:65], v[152:155], v[184:187], v[62:65]
	s_barrier
	v_mfma_f32_16x16x32_bf16 v[58:61], v[160:163], v[184:187], v[58:61]
	v_mfma_f32_16x16x32_bf16 v[46:49], v[152:155], v[192:195], v[46:49]
	v_mfma_f32_16x16x32_bf16 v[42:45], v[160:163], v[192:195], v[42:45]
	v_mfma_f32_16x16x32_bf16 v[30:33], v[152:155], v[200:203], v[30:33]
	v_mfma_f32_16x16x32_bf16 v[26:29], v[160:163], v[200:203], v[26:29]
	v_mfma_f32_16x16x32_bf16 v[14:17], v[152:155], v[214:217], v[14:17]
	v_mfma_f32_16x16x32_bf16 v[10:13], v[160:163], v[214:217], v[10:13]
	v_mfma_f32_16x16x32_bf16 v[54:57], v[168:171], v[184:187], v[54:57]
	v_mfma_f32_16x16x32_bf16 v[50:53], v[176:179], v[184:187], v[50:53]
	v_mfma_f32_16x16x32_bf16 v[38:41], v[168:171], v[192:195], v[38:41]
	v_mfma_f32_16x16x32_bf16 v[34:37], v[176:179], v[192:195], v[34:37]
	v_mfma_f32_16x16x32_bf16 v[22:25], v[168:171], v[200:203], v[22:25]
	v_mfma_f32_16x16x32_bf16 v[18:21], v[176:179], v[200:203], v[18:21]
	v_mfma_f32_16x16x32_bf16 v[6:9], v[168:171], v[214:217], v[6:9]
	v_mfma_f32_16x16x32_bf16 v[2:5], v[176:179], v[214:217], v[2:5]
	v_mfma_f32_16x16x32_bf16 v[62:65], v[156:159], v[188:191], v[62:65]
	v_mfma_f32_16x16x32_bf16 v[58:61], v[164:167], v[188:191], v[58:61]
	v_mfma_f32_16x16x32_bf16 v[46:49], v[156:159], v[196:199], v[46:49]
	v_mfma_f32_16x16x32_bf16 v[42:45], v[164:167], v[196:199], v[42:45]
	v_mfma_f32_16x16x32_bf16 v[30:33], v[156:159], v[204:207], v[30:33]
	v_mfma_f32_16x16x32_bf16 v[26:29], v[164:167], v[204:207], v[26:29]
	v_mfma_f32_16x16x32_bf16 v[14:17], v[156:159], v[218:221], v[14:17]
	v_mfma_f32_16x16x32_bf16 v[10:13], v[164:167], v[218:221], v[10:13]
	v_mfma_f32_16x16x32_bf16 v[54:57], v[172:175], v[188:191], v[54:57]
	v_mfma_f32_16x16x32_bf16 v[50:53], v[180:183], v[188:191], v[50:53]
	v_mfma_f32_16x16x32_bf16 v[38:41], v[172:175], v[196:199], v[38:41]
	v_mfma_f32_16x16x32_bf16 v[34:37], v[180:183], v[196:199], v[34:37]
	v_mfma_f32_16x16x32_bf16 v[22:25], v[172:175], v[204:207], v[22:25]
	v_mfma_f32_16x16x32_bf16 v[18:21], v[180:183], v[204:207], v[18:21]
	v_mfma_f32_16x16x32_bf16 v[6:9], v[172:175], v[218:221], v[6:9]
	v_mfma_f32_16x16x32_bf16 v[2:5], v[180:183], v[218:221], v[2:5]
	s_setprio 0
	s_barrier
	s_add_i32 s49, s49, 2
	s_add_u32 s20, s20, 0x100
	s_addc_u32 s21, s21, 0
	s_cmp_gt_u32 s49, 39
	s_cbranch_scc0 .LBB0_874
	s_lshl_b32 s82, s29, 19
	s_lshl_b32 s83, s10, 9
	s_add_u32 s80, s22, s82
	s_addc_u32 s81, s23, 0
	s_add_u32 s80, s80, s83
	s_addc_u32 s81, s81, 0
	v_and_b32_e32 v232, 15, v1
	s_lshr_b32 s82, s28, 2
	s_lshl_b32 s82, s82, 6
	v_lshrrev_b32_e32 v233, 4, v1
	v_add_u32_e32 v232, s82, v232
	s_and_b32 s83, s28, 3
	v_lshlrev_b32_e32 v233, 4, v233
	s_lshl_b32 s83, s83, 6
	v_lshlrev_b32_e32 v232, 11, v232
	v_add3_u32 v232, v232, v233, s83
	v_add_u32_e32 v164, s44, v150
	v_add_u32_e32 v180, s45, v150
	s_add_u32 s24, s12, s20
	ds_read_b128 v[152:155], v164
	ds_read_b128 v[156:159], v164 offset:1024
	ds_read_b128 v[160:163], v164 offset:2048
	ds_read_b128 v[164:167], v164 offset:3072
	ds_read_b128 v[168:171], v180
	ds_read_b128 v[172:175], v180 offset:1024
	ds_read_b128 v[176:179], v180 offset:2048
	ds_read_b128 v[180:183], v180 offset:3072
	s_addc_u32 s25, s13, s21
	s_add_u32 s24, s24, 0x100
	s_addc_u32 s25, s25, 0
	s_add_u32 s50, s17, s20
	s_addc_u32 s51, s48, s21
	s_cmpk_eq_i32 s20, 0x1500
	s_cselect_b32 s27, s19, s25
	s_cselect_b32 s26, s18, s24
	s_cselect_b32 s25, s7, s51
	s_cselect_b32 s24, s6, s50
	v_lshl_add_u64 v[208:209], v[146:147], 0, s[20:21]
	s_add_i32 m0, s37, 0xc000
	ds_read_b128 v[184:187], v151
	ds_read_b128 v[188:191], v151 offset:1024
	ds_read_b128 v[192:195], v151 offset:2048
	ds_read_b128 v[196:199], v151 offset:3072
	ds_read_b128 v[200:203], v151 offset:4096
	ds_read_b128 v[204:207], v151 offset:5120
	ds_read_b128 v[214:217], v151 offset:6144
	ds_read_b128 v[218:221], v151 offset:7168
	global_load_lds_dwordx4 v[208:209], off
	v_lshl_add_u64 v[208:209], v[148:149], 0, s[20:21]
	s_add_i32 m0, s37, 0xe000
	s_nop 0
	global_load_lds_dwordx4 v[208:209], off
	s_waitcnt vmcnt(8)
	s_waitcnt lgkmcnt(0)
	s_setprio 1
	s_waitcnt lgkmcnt(0)
	v_mfma_f32_16x16x32_bf16 v[126:129], v[152:155], v[184:187], v[126:129]
	s_barrier
	v_mfma_f32_16x16x32_bf16 v[122:125], v[160:163], v[184:187], v[122:125]
	v_mfma_f32_16x16x32_bf16 v[110:113], v[152:155], v[192:195], v[110:113]
	v_mfma_f32_16x16x32_bf16 v[106:109], v[160:163], v[192:195], v[106:109]
	v_mfma_f32_16x16x32_bf16 v[94:97], v[152:155], v[200:203], v[94:97]
	v_mfma_f32_16x16x32_bf16 v[90:93], v[160:163], v[200:203], v[90:93]
	v_mfma_f32_16x16x32_bf16 v[78:81], v[152:155], v[214:217], v[78:81]
	v_mfma_f32_16x16x32_bf16 v[74:77], v[160:163], v[214:217], v[74:77]
	v_mfma_f32_16x16x32_bf16 v[118:121], v[168:171], v[184:187], v[118:121]
	v_mfma_f32_16x16x32_bf16 v[114:117], v[176:179], v[184:187], v[114:117]
	v_mfma_f32_16x16x32_bf16 v[102:105], v[168:171], v[192:195], v[102:105]
	v_mfma_f32_16x16x32_bf16 v[98:101], v[176:179], v[192:195], v[98:101]
	v_mfma_f32_16x16x32_bf16 v[86:89], v[168:171], v[200:203], v[86:89]
	v_mfma_f32_16x16x32_bf16 v[82:85], v[176:179], v[200:203], v[82:85]
	v_mfma_f32_16x16x32_bf16 v[70:73], v[168:171], v[214:217], v[70:73]
	v_mfma_f32_16x16x32_bf16 v[66:69], v[176:179], v[214:217], v[66:69]
	v_mfma_f32_16x16x32_bf16 v[126:129], v[156:159], v[188:191], v[126:129]
	v_mfma_f32_16x16x32_bf16 v[122:125], v[164:167], v[188:191], v[122:125]
	v_mfma_f32_16x16x32_bf16 v[110:113], v[156:159], v[196:199], v[110:113]
	v_mfma_f32_16x16x32_bf16 v[106:109], v[164:167], v[196:199], v[106:109]
	v_mfma_f32_16x16x32_bf16 v[94:97], v[156:159], v[204:207], v[94:97]
	v_mfma_f32_16x16x32_bf16 v[90:93], v[164:167], v[204:207], v[90:93]
	v_mfma_f32_16x16x32_bf16 v[78:81], v[156:159], v[218:221], v[78:81]
	v_mfma_f32_16x16x32_bf16 v[74:77], v[164:167], v[218:221], v[74:77]
	v_mfma_f32_16x16x32_bf16 v[118:121], v[172:175], v[188:191], v[118:121]
	v_mfma_f32_16x16x32_bf16 v[114:117], v[180:183], v[188:191], v[114:117]
	v_mfma_f32_16x16x32_bf16 v[102:105], v[172:175], v[196:199], v[102:105]
	v_mfma_f32_16x16x32_bf16 v[98:101], v[180:183], v[196:199], v[98:101]
	v_mfma_f32_16x16x32_bf16 v[86:89], v[172:175], v[204:207], v[86:89]
	v_mfma_f32_16x16x32_bf16 v[82:85], v[180:183], v[204:207], v[82:85]
	v_mfma_f32_16x16x32_bf16 v[70:73], v[172:175], v[218:221], v[70:73]
	v_mfma_f32_16x16x32_bf16 v[66:69], v[180:183], v[218:221], v[66:69]
	s_setprio 0
	s_barrier
	s_add_i32 s50, s44, s36
	v_lshl_add_u64 v[208:209], s[24:25], 0, v[132:133]
	s_mov_b32 m0, s50
	ds_read_b128 v[184:187], v151 offset:16384
	ds_read_b128 v[188:191], v151 offset:17408
	ds_read_b128 v[192:195], v151 offset:18432
	ds_read_b128 v[196:199], v151 offset:19456
	ds_read_b128 v[200:203], v151 offset:20480
	ds_read_b128 v[204:207], v151 offset:21504
	ds_read_b128 v[214:217], v151 offset:22528
	ds_read_b128 v[218:221], v151 offset:23552
	s_add_u32 s84, s80, 0x0
	s_addc_u32 s85, s81, 0
	global_load_lds_dwordx4 v232, s[84:85]
	s_add_i32 m0, s50, 0x2000
	s_add_u32 s50, s24, 0xb0000
	v_lshl_add_u64 v[222:223], s[24:25], 0, v[136:137]
	s_addc_u32 s51, s25, 0
	s_add_i32 s56, s45, s36
	s_add_u32 s84, s80, 0x100
	s_addc_u32 s85, s81, 0
	global_load_lds_dwordx4 v232, s[84:85]
	v_lshl_add_u64 v[224:225], s[50:51], 0, v[132:133]
	s_mov_b32 m0, s56
	v_lshl_add_u64 v[226:227], s[26:27], 0, v[134:135]
	s_add_u32 s84, s80, 0x8000
	s_addc_u32 s85, s81, 0
	global_load_lds_dwordx4 v232, s[84:85]
	v_lshl_add_u64 v[224:225], s[50:51], 0, v[136:137]
	s_add_i32 m0, s56, 0x2000
	s_nop 0
	s_add_u32 s84, s80, 0x8100
	s_addc_u32 s85, s81, 0
	global_load_lds_dwordx4 v232, s[84:85]
	v_lshl_add_u64 v[224:225], s[26:27], 0, v[130:131]
	s_mov_b32 m0, s37
	s_nop 0
	s_add_u32 s84, s80, 0x10000
	s_addc_u32 s85, s81, 0
	global_load_lds_dwordx4 v232, s[84:85]
	s_mov_b32 m0, s38
	s_nop 0
	s_add_u32 s84, s80, 0x10100
	s_addc_u32 s85, s81, 0
	global_load_lds_dwordx4 v232, s[84:85]
	s_waitcnt vmcnt(8)
	s_waitcnt lgkmcnt(0)
	s_setprio 1
	s_waitcnt lgkmcnt(0)
	v_mfma_f32_16x16x32_bf16 v[62:65], v[152:155], v[184:187], v[62:65]
	s_barrier
	v_mfma_f32_16x16x32_bf16 v[58:61], v[160:163], v[184:187], v[58:61]
	v_mfma_f32_16x16x32_bf16 v[46:49], v[152:155], v[192:195], v[46:49]
	v_mfma_f32_16x16x32_bf16 v[42:45], v[160:163], v[192:195], v[42:45]
	v_mfma_f32_16x16x32_bf16 v[30:33], v[152:155], v[200:203], v[30:33]
	v_mfma_f32_16x16x32_bf16 v[26:29], v[160:163], v[200:203], v[26:29]
	v_mfma_f32_16x16x32_bf16 v[14:17], v[152:155], v[214:217], v[14:17]
	v_mfma_f32_16x16x32_bf16 v[10:13], v[160:163], v[214:217], v[10:13]
	v_mfma_f32_16x16x32_bf16 v[54:57], v[168:171], v[184:187], v[54:57]
	v_mfma_f32_16x16x32_bf16 v[50:53], v[176:179], v[184:187], v[50:53]
	v_mfma_f32_16x16x32_bf16 v[38:41], v[168:171], v[192:195], v[38:41]
	v_mfma_f32_16x16x32_bf16 v[34:37], v[176:179], v[192:195], v[34:37]
	v_mfma_f32_16x16x32_bf16 v[22:25], v[168:171], v[200:203], v[22:25]
	v_mfma_f32_16x16x32_bf16 v[18:21], v[176:179], v[200:203], v[18:21]
	v_mfma_f32_16x16x32_bf16 v[6:9], v[168:171], v[214:217], v[6:9]
	v_mfma_f32_16x16x32_bf16 v[2:5], v[176:179], v[214:217], v[2:5]
	v_mfma_f32_16x16x32_bf16 v[62:65], v[156:159], v[188:191], v[62:65]
	v_mfma_f32_16x16x32_bf16 v[58:61], v[164:167], v[188:191], v[58:61]
	v_mfma_f32_16x16x32_bf16 v[46:49], v[156:159], v[196:199], v[46:49]
	v_mfma_f32_16x16x32_bf16 v[42:45], v[164:167], v[196:199], v[42:45]
	v_mfma_f32_16x16x32_bf16 v[30:33], v[156:159], v[204:207], v[30:33]
	v_mfma_f32_16x16x32_bf16 v[26:29], v[164:167], v[204:207], v[26:29]
	v_mfma_f32_16x16x32_bf16 v[14:17], v[156:159], v[218:221], v[14:17]
	v_mfma_f32_16x16x32_bf16 v[10:13], v[164:167], v[218:221], v[10:13]
	v_mfma_f32_16x16x32_bf16 v[54:57], v[172:175], v[188:191], v[54:57]
	v_mfma_f32_16x16x32_bf16 v[50:53], v[180:183], v[188:191], v[50:53]
	v_mfma_f32_16x16x32_bf16 v[38:41], v[172:175], v[196:199], v[38:41]
	v_mfma_f32_16x16x32_bf16 v[34:37], v[180:183], v[196:199], v[34:37]
	v_mfma_f32_16x16x32_bf16 v[22:25], v[172:175], v[204:207], v[22:25]
	v_mfma_f32_16x16x32_bf16 v[18:21], v[180:183], v[204:207], v[18:21]
	v_mfma_f32_16x16x32_bf16 v[6:9], v[172:175], v[218:221], v[6:9]
	v_mfma_f32_16x16x32_bf16 v[2:5], v[180:183], v[218:221], v[2:5]
	s_setprio 0
	s_barrier
	s_add_i32 s50, 0, 0x18000
	s_add_i32 s51, 0, 0x1c000
	v_add_u32_e32 v164, s50, v150
	v_add_u32_e32 v180, s51, v150
	ds_read_b128 v[152:155], v164
	ds_read_b128 v[156:159], v164 offset:1024
	ds_read_b128 v[160:163], v164 offset:2048
	ds_read_b128 v[164:167], v164 offset:3072
	ds_read_b128 v[168:171], v180
	ds_read_b128 v[172:175], v180 offset:1024
	ds_read_b128 v[176:179], v180 offset:2048
	ds_read_b128 v[180:183], v180 offset:3072
	s_add_u32 s26, s26, 0xb0000
	s_addc_u32 s27, s27, 0
	s_mov_b32 m0, s39
	v_lshl_add_u64 v[228:229], s[26:27], 0, v[130:131]
	ds_read_b128 v[184:187], v151 offset:32768
	ds_read_b128 v[188:191], v151 offset:33792
	ds_read_b128 v[192:195], v151 offset:34816
	ds_read_b128 v[196:199], v151 offset:35840
	ds_read_b128 v[200:203], v151 offset:36864
	ds_read_b128 v[204:207], v151 offset:37888
	ds_read_b128 v[214:217], v151 offset:38912
	ds_read_b128 v[218:221], v151 offset:39936
	s_add_u32 s84, s80, 0x18000
	s_addc_u32 s85, s81, 0
	global_load_lds_dwordx4 v232, s[84:85]
	v_lshl_add_u64 v[228:229], s[26:27], 0, v[134:135]
	s_mov_b32 m0, s40
	s_nop 0
	s_add_u32 s84, s80, 0x18100
	s_addc_u32 s85, s81, 0
	global_load_lds_dwordx4 v232, s[84:85]
	s_waitcnt vmcnt(8)
	s_waitcnt lgkmcnt(0)
	s_setprio 1
	s_waitcnt lgkmcnt(0)
	v_mfma_f32_16x16x32_bf16 v[126:129], v[152:155], v[184:187], v[126:129]
	s_barrier
	v_mfma_f32_16x16x32_bf16 v[122:125], v[160:163], v[184:187], v[122:125]
	v_mfma_f32_16x16x32_bf16 v[110:113], v[152:155], v[192:195], v[110:113]
	v_mfma_f32_16x16x32_bf16 v[106:109], v[160:163], v[192:195], v[106:109]
	v_mfma_f32_16x16x32_bf16 v[94:97], v[152:155], v[200:203], v[94:97]
	v_mfma_f32_16x16x32_bf16 v[90:93], v[160:163], v[200:203], v[90:93]
	v_mfma_f32_16x16x32_bf16 v[78:81], v[152:155], v[214:217], v[78:81]
	v_mfma_f32_16x16x32_bf16 v[74:77], v[160:163], v[214:217], v[74:77]
	v_mfma_f32_16x16x32_bf16 v[118:121], v[168:171], v[184:187], v[118:121]
	v_mfma_f32_16x16x32_bf16 v[114:117], v[176:179], v[184:187], v[114:117]
	v_mfma_f32_16x16x32_bf16 v[102:105], v[168:171], v[192:195], v[102:105]
	v_mfma_f32_16x16x32_bf16 v[98:101], v[176:179], v[192:195], v[98:101]
	v_mfma_f32_16x16x32_bf16 v[86:89], v[168:171], v[200:203], v[86:89]
	v_mfma_f32_16x16x32_bf16 v[82:85], v[176:179], v[200:203], v[82:85]
	v_mfma_f32_16x16x32_bf16 v[70:73], v[168:171], v[214:217], v[70:73]
	v_mfma_f32_16x16x32_bf16 v[66:69], v[176:179], v[214:217], v[66:69]
	v_mfma_f32_16x16x32_bf16 v[126:129], v[156:159], v[188:191], v[126:129]
	v_mfma_f32_16x16x32_bf16 v[122:125], v[164:167], v[188:191], v[122:125]
	v_mfma_f32_16x16x32_bf16 v[110:113], v[156:159], v[196:199], v[110:113]
	v_mfma_f32_16x16x32_bf16 v[106:109], v[164:167], v[196:199], v[106:109]
	v_mfma_f32_16x16x32_bf16 v[94:97], v[156:159], v[204:207], v[94:97]
	v_mfma_f32_16x16x32_bf16 v[90:93], v[164:167], v[204:207], v[90:93]
	v_mfma_f32_16x16x32_bf16 v[78:81], v[156:159], v[218:221], v[78:81]
	v_mfma_f32_16x16x32_bf16 v[74:77], v[164:167], v[218:221], v[74:77]
	v_mfma_f32_16x16x32_bf16 v[118:121], v[172:175], v[188:191], v[118:121]
	v_mfma_f32_16x16x32_bf16 v[114:117], v[180:183], v[188:191], v[114:117]
	v_mfma_f32_16x16x32_bf16 v[102:105], v[172:175], v[196:199], v[102:105]
	v_mfma_f32_16x16x32_bf16 v[98:101], v[180:183], v[196:199], v[98:101]
	v_mfma_f32_16x16x32_bf16 v[86:89], v[172:175], v[204:207], v[86:89]
	v_mfma_f32_16x16x32_bf16 v[82:85], v[180:183], v[204:207], v[82:85]
	v_mfma_f32_16x16x32_bf16 v[70:73], v[172:175], v[218:221], v[70:73]
	v_mfma_f32_16x16x32_bf16 v[66:69], v[180:183], v[218:221], v[66:69]
	s_setprio 0
	s_barrier
	s_add_i32 s26, s50, s36
	v_lshl_add_u64 v[208:209], v[208:209], 0, s[14:15]
	s_mov_b32 m0, s26
	ds_read_b128 v[184:187], v151 offset:49152
	ds_read_b128 v[188:191], v151 offset:50176
	ds_read_b128 v[192:195], v151 offset:51200
	ds_read_b128 v[196:199], v151 offset:52224
	ds_read_b128 v[200:203], v151 offset:53248
	ds_read_b128 v[204:207], v151 offset:54272
	ds_read_b128 v[214:217], v151 offset:55296
	ds_read_b128 v[218:221], v151 offset:56320
	s_add_u32 s84, s80, 0x40000
	s_addc_u32 s85, s81, 0
	global_load_lds_dwordx4 v232, s[84:85]
	s_add_i32 m0, s26, 0x2000
	s_add_u32 s24, s24, 0xb0080
	v_lshl_add_u64 v[208:209], v[222:223], 0, s[14:15]
	s_addc_u32 s25, s25, 0
	s_add_i32 s26, s51, s36
	s_add_u32 s84, s80, 0x40100
	s_addc_u32 s85, s81, 0
	global_load_lds_dwordx4 v232, s[84:85]
	v_lshl_add_u64 v[208:209], s[24:25], 0, v[132:133]
	s_mov_b32 m0, s26
	s_nop 0
	s_add_u32 s84, s80, 0x48000
	s_addc_u32 s85, s81, 0
	global_load_lds_dwordx4 v232, s[84:85]
	v_lshl_add_u64 v[208:209], s[24:25], 0, v[136:137]
	s_add_i32 m0, s26, 0x2000
	s_nop 0
	s_add_u32 s84, s80, 0x48100
	s_addc_u32 s85, s81, 0
	global_load_lds_dwordx4 v232, s[84:85]
	v_lshl_add_u64 v[208:209], v[224:225], 0, s[14:15]
	s_mov_b32 m0, s41
	s_nop 0
	s_add_u32 s84, s80, 0x50000
	s_addc_u32 s85, s81, 0
	global_load_lds_dwordx4 v232, s[84:85]
	v_lshl_add_u64 v[208:209], v[226:227], 0, s[14:15]
	s_mov_b32 m0, s42
	s_nop 0
	s_add_u32 s84, s80, 0x50100
	s_addc_u32 s85, s81, 0
	global_load_lds_dwordx4 v232, s[84:85]
	s_waitcnt vmcnt(8)
	s_waitcnt lgkmcnt(0)
	s_setprio 1
	s_waitcnt lgkmcnt(0)
	v_mfma_f32_16x16x32_bf16 v[62:65], v[152:155], v[184:187], v[62:65]
	s_barrier
	v_mfma_f32_16x16x32_bf16 v[58:61], v[160:163], v[184:187], v[58:61]
	v_mfma_f32_16x16x32_bf16 v[46:49], v[152:155], v[192:195], v[46:49]
	v_mfma_f32_16x16x32_bf16 v[42:45], v[160:163], v[192:195], v[42:45]
	v_mfma_f32_16x16x32_bf16 v[30:33], v[152:155], v[200:203], v[30:33]
	v_mfma_f32_16x16x32_bf16 v[26:29], v[160:163], v[200:203], v[26:29]
	v_mfma_f32_16x16x32_bf16 v[14:17], v[152:155], v[214:217], v[14:17]
	v_mfma_f32_16x16x32_bf16 v[10:13], v[160:163], v[214:217], v[10:13]
	v_mfma_f32_16x16x32_bf16 v[54:57], v[168:171], v[184:187], v[54:57]
	v_mfma_f32_16x16x32_bf16 v[50:53], v[176:179], v[184:187], v[50:53]
	v_mfma_f32_16x16x32_bf16 v[38:41], v[168:171], v[192:195], v[38:41]
	v_mfma_f32_16x16x32_bf16 v[34:37], v[176:179], v[192:195], v[34:37]
	v_mfma_f32_16x16x32_bf16 v[22:25], v[168:171], v[200:203], v[22:25]
	v_mfma_f32_16x16x32_bf16 v[18:21], v[176:179], v[200:203], v[18:21]
	v_mfma_f32_16x16x32_bf16 v[6:9], v[168:171], v[214:217], v[6:9]
	v_mfma_f32_16x16x32_bf16 v[2:5], v[176:179], v[214:217], v[2:5]
	v_mfma_f32_16x16x32_bf16 v[62:65], v[156:159], v[188:191], v[62:65]
	v_mfma_f32_16x16x32_bf16 v[58:61], v[164:167], v[188:191], v[58:61]
	v_mfma_f32_16x16x32_bf16 v[46:49], v[156:159], v[196:199], v[46:49]
	v_mfma_f32_16x16x32_bf16 v[42:45], v[164:167], v[196:199], v[42:45]
	v_mfma_f32_16x16x32_bf16 v[30:33], v[156:159], v[204:207], v[30:33]
	v_mfma_f32_16x16x32_bf16 v[26:29], v[164:167], v[204:207], v[26:29]
	v_mfma_f32_16x16x32_bf16 v[14:17], v[156:159], v[218:221], v[14:17]
	v_mfma_f32_16x16x32_bf16 v[10:13], v[164:167], v[218:221], v[10:13]
	v_mfma_f32_16x16x32_bf16 v[54:57], v[172:175], v[188:191], v[54:57]
	v_mfma_f32_16x16x32_bf16 v[50:53], v[180:183], v[188:191], v[50:53]
	v_mfma_f32_16x16x32_bf16 v[38:41], v[172:175], v[196:199], v[38:41]
	v_mfma_f32_16x16x32_bf16 v[34:37], v[180:183], v[196:199], v[34:37]
	v_mfma_f32_16x16x32_bf16 v[22:25], v[172:175], v[204:207], v[22:25]
	v_mfma_f32_16x16x32_bf16 v[18:21], v[180:183], v[204:207], v[18:21]
	v_mfma_f32_16x16x32_bf16 v[6:9], v[172:175], v[218:221], v[6:9]
	v_mfma_f32_16x16x32_bf16 v[2:5], v[180:183], v[218:221], v[2:5]
	s_setprio 0
	s_barrier
	s_add_i32 s49, s49, 2
	s_add_u32 s20, s20, 0x100
	s_addc_u32 s21, s21, 0
	s_add_u32 s20, s17, 0xffffff00
	s_addc_u32 s21, s48, -1
	s_and_b64 vcc, exec, s[4:5]
	s_cbranch_vccnz .LBB0_877
	v_mov_b32_e32 v2, 0
	s_mov_b32 s10, s46
	s_mov_b32 s29, s47
	s_mov_b64 s[12:13], s[18:19]
	s_mov_b32 s43, s16
	v_mov_b32_e32 v3, v2
	v_mov_b32_e32 v4, v2
	v_mov_b32_e32 v5, v2
	v_mov_b32_e32 v6, v2
	v_mov_b32_e32 v7, v2
	v_mov_b32_e32 v8, v2
	v_mov_b32_e32 v9, v2
	v_mov_b32_e32 v18, v2
	v_mov_b32_e32 v19, v2
	v_mov_b32_e32 v20, v2
	v_mov_b32_e32 v21, v2
	v_mov_b32_e32 v22, v2
	v_mov_b32_e32 v23, v2
	v_mov_b32_e32 v24, v2
	v_mov_b32_e32 v25, v2
	v_mov_b32_e32 v34, v2
	v_mov_b32_e32 v35, v2
	v_mov_b32_e32 v36, v2
	v_mov_b32_e32 v37, v2
	v_mov_b32_e32 v38, v2
	v_mov_b32_e32 v39, v2
	v_mov_b32_e32 v40, v2
	v_mov_b32_e32 v41, v2
	v_mov_b32_e32 v50, v2
	v_mov_b32_e32 v51, v2
	v_mov_b32_e32 v52, v2
	v_mov_b32_e32 v53, v2
	v_mov_b32_e32 v54, v2
	v_mov_b32_e32 v55, v2
	v_mov_b32_e32 v56, v2
	v_mov_b32_e32 v57, v2
	v_mov_b32_e32 v10, v2
	v_mov_b32_e32 v11, v2
	v_mov_b32_e32 v12, v2
	v_mov_b32_e32 v13, v2
	v_mov_b32_e32 v14, v2
	v_mov_b32_e32 v15, v2
	v_mov_b32_e32 v16, v2
	v_mov_b32_e32 v17, v2
	v_mov_b32_e32 v26, v2
	v_mov_b32_e32 v27, v2
	v_mov_b32_e32 v28, v2
	v_mov_b32_e32 v29, v2
	v_mov_b32_e32 v30, v2
	v_mov_b32_e32 v31, v2
	v_mov_b32_e32 v32, v2
	v_mov_b32_e32 v33, v2
	v_mov_b32_e32 v42, v2
	v_mov_b32_e32 v43, v2
	v_mov_b32_e32 v44, v2
	v_mov_b32_e32 v45, v2
	v_mov_b32_e32 v46, v2
	v_mov_b32_e32 v47, v2
	v_mov_b32_e32 v48, v2
	v_mov_b32_e32 v49, v2
	v_mov_b32_e32 v58, v2
	v_mov_b32_e32 v59, v2
	v_mov_b32_e32 v60, v2
	v_mov_b32_e32 v61, v2
	v_mov_b32_e32 v62, v2
	v_mov_b32_e32 v63, v2
	v_mov_b32_e32 v64, v2
	v_mov_b32_e32 v65, v2
	v_mov_b32_e32 v66, v2
	v_mov_b32_e32 v67, v2
	v_mov_b32_e32 v68, v2
	v_mov_b32_e32 v69, v2
	v_mov_b32_e32 v70, v2
	v_mov_b32_e32 v71, v2
	v_mov_b32_e32 v72, v2
	v_mov_b32_e32 v73, v2
	v_mov_b32_e32 v82, v2
	v_mov_b32_e32 v83, v2
	v_mov_b32_e32 v84, v2
	v_mov_b32_e32 v85, v2
	v_mov_b32_e32 v86, v2
	v_mov_b32_e32 v87, v2
	v_mov_b32_e32 v88, v2
	v_mov_b32_e32 v89, v2
	v_mov_b32_e32 v98, v2
	v_mov_b32_e32 v99, v2
	v_mov_b32_e32 v100, v2
	v_mov_b32_e32 v101, v2
	v_mov_b32_e32 v102, v2
	v_mov_b32_e32 v103, v2
	v_mov_b32_e32 v104, v2
	v_mov_b32_e32 v105, v2
	v_mov_b32_e32 v114, v2
	v_mov_b32_e32 v115, v2
	v_mov_b32_e32 v116, v2
	v_mov_b32_e32 v117, v2
	v_mov_b32_e32 v118, v2
	v_mov_b32_e32 v119, v2
	v_mov_b32_e32 v120, v2
	v_mov_b32_e32 v121, v2
	v_mov_b32_e32 v74, v2
	v_mov_b32_e32 v75, v2
	v_mov_b32_e32 v76, v2
	v_mov_b32_e32 v77, v2
	v_mov_b32_e32 v78, v2
	v_mov_b32_e32 v79, v2
	v_mov_b32_e32 v80, v2
	v_mov_b32_e32 v81, v2
	v_mov_b32_e32 v90, v2
	v_mov_b32_e32 v91, v2
	v_mov_b32_e32 v92, v2
	v_mov_b32_e32 v93, v2
	v_mov_b32_e32 v94, v2
	v_mov_b32_e32 v95, v2
	v_mov_b32_e32 v96, v2
	v_mov_b32_e32 v97, v2
	v_mov_b32_e32 v106, v2
	v_mov_b32_e32 v107, v2
	v_mov_b32_e32 v108, v2
	v_mov_b32_e32 v109, v2
	v_mov_b32_e32 v110, v2
	v_mov_b32_e32 v111, v2
	v_mov_b32_e32 v112, v2
	v_mov_b32_e32 v113, v2
	v_mov_b32_e32 v122, v2
	v_mov_b32_e32 v123, v2
	v_mov_b32_e32 v124, v2
	v_mov_b32_e32 v125, v2
	v_mov_b32_e32 v126, v2
	v_mov_b32_e32 v127, v2
	v_mov_b32_e32 v128, v2
	v_mov_b32_e32 v129, v2
	s_andn2_b64 vcc, exec, s[0:1]
	s_cbranch_vccnz .LBB0_878
	s_branch .LBB0_879

.LBB0_881:
	v_lshrrev_b32_e32 v214, 4, v1
	s_lshl_b32 s6, s10, 8
	s_lshl_b32 s2, s29, 8
	s_lshl_b32 s18, s31, 5
	v_lshl_or_b32 v130, v214, 3, s6
	s_add_i32 s4, s2, s30
	v_or_b32_e32 v178, s18, v130
	v_or_b32_e32 v130, s4, v213
	v_ashrrev_i32_e32 v179, 31, v178
	v_ashrrev_i32_e32 v131, 31, v130
	v_lshl_add_u64 v[132:133], v[178:179], 1, s[22:23]
	v_lshlrev_b64 v[134:135], 11, v[130:131]
	v_lshl_add_u64 v[134:135], v[132:133], 0, v[134:135]
	s_barrier
	v_lshlrev_b32_e32 v234, 4, v1
	v_add_u32_e32 v234, s36, v234
	v_add_u32_e32 v235, 0x10000, v234
	ds_read_b128 v[206:209], v235 offset:0
	ds_read_b128 v[202:205], v235 offset:8192
	v_or_b32_e32 v134, 16, v130
	v_ashrrev_i32_e32 v135, 31, v134
	v_lshlrev_b64 v[134:135], 11, v[134:135]
	v_lshl_add_u64 v[134:135], v[132:133], 0, v[134:135]
	ds_read_b128 v[198:201], v235 offset:16384
	ds_read_b128 v[186:189], v235 offset:24576
	v_or_b32_e32 v134, 32, v130
	v_ashrrev_i32_e32 v135, 31, v134
	v_lshlrev_b64 v[134:135], 11, v[134:135]
	v_lshl_add_u64 v[134:135], v[132:133], 0, v[134:135]
	ds_read_b128 v[174:177], v234 offset:0
	ds_read_b128 v[170:173], v234 offset:8192
	v_or_b32_e32 v134, 48, v130
	v_ashrrev_i32_e32 v135, 31, v134
	v_lshlrev_b64 v[134:135], 11, v[134:135]
	v_lshl_add_u64 v[134:135], v[132:133], 0, v[134:135]
	ds_read_b128 v[166:169], v234 offset:16384
	ds_read_b128 v[162:165], v234 offset:24576
	v_add_u32_e32 v134, 0x80, v130
	v_ashrrev_i32_e32 v135, 31, v134
	v_lshlrev_b64 v[134:135], 11, v[134:135]
	v_lshl_add_u64 v[134:135], v[132:133], 0, v[134:135]
	ds_read_b128 v[158:161], v235 offset:32768
	ds_read_b128 v[154:157], v235 offset:40960
	v_add_u32_e32 v134, 0x90, v130
	v_ashrrev_i32_e32 v135, 31, v134
	v_lshlrev_b64 v[134:135], 11, v[134:135]
	v_lshl_add_u64 v[134:135], v[132:133], 0, v[134:135]
	ds_read_b128 v[150:153], v235 offset:49152
	ds_read_b128 v[146:149], v235 offset:57344
	v_add_u32_e32 v134, 0xa0, v130
	v_add_u32_e32 v130, 0xb0, v130
	v_ashrrev_i32_e32 v135, 31, v134
	v_ashrrev_i32_e32 v131, 31, v130
	v_lshlrev_b64 v[134:135], 11, v[134:135]
	v_lshlrev_b64 v[130:131], 11, v[130:131]
	v_lshl_add_u64 v[134:135], v[132:133], 0, v[134:135]
	v_lshl_add_u64 v[130:131], v[132:133], 0, v[130:131]
	ds_read_b128 v[142:145], v234 offset:32768
	ds_read_b128 v[138:141], v234 offset:40960
	s_nop 0
	global_load_dwordx4 v[134:137], v[130:131], off
	s_nop 0
	global_load_dwordx4 v[130:133], v[130:131], off offset:256
	s_waitcnt lgkmcnt(0)
	s_barrier
	v_mul_f32_e32 v183, v127, v127
	v_mul_f32_e32 v184, v129, v129
	v_fmac_f32_e32 v183, v126, v126
	v_fmac_f32_e32 v184, v128, v128
	v_add_f32_e32 v183, v183, v184
	v_mul_f32_e32 v184, v123, v123
	v_mul_f32_e32 v185, v125, v125
	v_fmac_f32_e32 v184, v122, v122
	v_fmac_f32_e32 v185, v124, v124
	v_add_f32_e32 v184, v184, v185
	v_mbcnt_lo_u32_b32 v180, -1, 0
	v_add_f32_e32 v183, v184, v183
	v_mul_f32_e32 v184, v119, v119
	v_mul_f32_e32 v185, v121, v121
	v_mbcnt_hi_u32_b32 v181, -1, v180
	v_fmac_f32_e32 v184, v118, v118
	v_fmac_f32_e32 v185, v120, v120
	v_and_b32_e32 v182, 64, v181
	v_add_f32_e32 v184, v184, v185
	v_xor_b32_e32 v180, 16, v181
	v_add_u32_e32 v182, 64, v182
	v_add_f32_e32 v183, v184, v183
	v_mul_f32_e32 v184, v115, v115
	v_mul_f32_e32 v185, v117, v117
	v_cmp_lt_i32_e32 vcc, v180, v182
	v_fmac_f32_e32 v184, v114, v114
	v_fmac_f32_e32 v185, v116, v116
	v_cndmask_b32_e32 v180, v181, v180, vcc
	v_add_f32_e32 v184, v184, v185
	v_lshlrev_b32_e32 v180, 2, v180
	v_add_f32_e32 v183, v184, v183
	ds_bpermute_b32 v184, v180, v183
	v_xor_b32_e32 v185, 32, v181
	v_cmp_lt_i32_e32 vcc, v185, v182
	s_lshl_b32 s0, s31, 2
	s_add_i32 s3, s0, 0
	v_cndmask_b32_e32 v181, v181, v185, vcc
	v_lshlrev_b32_e32 v181, 2, v181
	s_waitcnt lgkmcnt(0)
	v_add_f32_e32 v182, v183, v184
	ds_bpermute_b32 v183, v181, v182
	v_cmp_gt_u32_e32 vcc, 16, v1
	s_and_saveexec_b64 s[0:1], vcc
	s_cbranch_execz .LBB0_883
	s_lshl_b32 s5, s11, 10
	s_add_i32 s5, s3, s5
	v_lshl_add_u32 v184, v213, 4, s5
	s_waitcnt lgkmcnt(0)
	v_add_f32_e32 v182, v182, v183
	ds_write_b32 v184, v182
